# ret_scan cross GEMM: two row-blocks per pass share each packed state fragment (halves v_cvt_pk count), integer RNE + d16_hi store for single-element output conversion
# baseline (speedup 1.0000x reference)
.LBB0_327:
	v_mov_b32_e32 v130, s67
	v_mov_b32_e32 v131, s66
	v_cndmask_b32_e32 v130, v130, v131, vcc
	v_lshl_add_u32 v168, v130, 7, v155
	v_mov_b32_e32 v153, v161
	v_mov_b32_e32 v192, v181
	v_mov_b32_e32 v190, v183
	v_mov_b32_e32 v191, v182
	v_mov_b32_e32 v166, v157
	v_mov_b32_e32 v130, v186
	v_mov_b32_e32 v131, v187
	v_ashrrev_i32_e32 v169, 31, v168
	v_readfirstlane_b32 s64, v130
	v_readfirstlane_b32 s65, v131
	v_lshlrev_b64 v[130:131], 11, v[168:169]
	v_mov_b32_e32 v167, v189
	s_barrier
	v_lshl_add_u64 v[130:131], s[64:65], 0, v[130:131]
	v_lshl_add_u64 v[130:131], v[130:131], 0, v[0:1]
	v_lshlrev_b32_e32 v132, 4, v167
	v_and_b32_e32 v198, 0x1f0, v132
	v_mov_b32_e32 v199, v1
	v_lshlrev_b32_e32 v132, 6, v167
	v_lshl_add_u64 v[130:131], v[130:131], 0, v[198:199]
	v_and_b32_e32 v132, 0x3800, v132
	v_mov_b32_e32 v133, v1
	v_lshl_add_u64 v[208:209], v[130:131], 0, v[132:133]
	s_mov_b32 s6, 0xc640000
	v_add_co_u32_e64 v130, s[6:7], s6, v208
	v_bfe_u32 v167, v167, 5, 3
	s_nop 0
	v_addc_co_u32_e64 v131, s[6:7], 0, v209, s[6:7]
	s_mov_b32 s6, 0xc644000
	s_nop 0
	v_add_co_u32_e64 v134, s[6:7], s6, v208
	v_mul_u32_u24_e32 v167, 0x208, v167
	s_nop 0
	v_addc_co_u32_e64 v135, s[6:7], 0, v209, s[6:7]
	s_mov_b32 s6, 0xc648000
	s_nop 0
	v_add_co_u32_e64 v138, s[6:7], s6, v208
	global_load_dwordx4 v[130:133], v[130:131], off
	s_nop 0
	global_load_dwordx4 v[134:137], v[134:135], off
	v_addc_co_u32_e64 v139, s[6:7], 0, v209, s[6:7]
	s_mov_b32 s6, 0xc64c000
	s_nop 0
	v_add_co_u32_e64 v142, s[6:7], s6, v208
	v_add3_u32 v167, v149, v198, v167
	s_nop 0
	v_addc_co_u32_e64 v143, s[6:7], 0, v209, s[6:7]
	s_mov_b32 s6, 0xc650000
	s_nop 0
	v_add_co_u32_e64 v170, s[6:7], s6, v208
	global_load_dwordx4 v[138:141], v[138:139], off
	s_nop 0
	global_load_dwordx4 v[142:145], v[142:143], off
	v_addc_co_u32_e64 v171, s[6:7], 0, v209, s[6:7]
	s_mov_b32 s6, 0xc654000
	s_nop 0
	v_add_co_u32_e64 v194, s[6:7], s6, v208
	v_add_u32_e32 v193, 0x1040, v167
	s_nop 0
	v_addc_co_u32_e64 v195, s[6:7], 0, v209, s[6:7]
	s_mov_b32 s6, 0xc658000
	s_nop 0
	v_add_co_u32_e64 v210, s[6:7], s6, v208
	global_load_dwordx4 v[170:173], v[170:171], off
	s_nop 0
	global_load_dwordx4 v[194:197], v[194:195], off
	v_addc_co_u32_e64 v211, s[6:7], 0, v209, s[6:7]
	s_mov_b32 s6, 0xc65c000
	global_load_dwordx4 v[218:221], v[210:211], off
	v_add_co_u32_e64 v210, s[6:7], s6, v208
	v_add_u32_e32 v198, 0x2080, v167
	s_nop 0
	v_addc_co_u32_e64 v211, s[6:7], 0, v209, s[6:7]
	global_load_dwordx4 v[222:225], v[210:211], off
	v_add_u32_e32 v199, 0x30c0, v167
	v_add_u32_e32 v201, 0x4100, v167
	v_add_u32_e32 v217, 0x5140, v167
	v_lshl_add_u64 v[210:211], s[64:65], 0, v[162:163]
	s_waitcnt vmcnt(7)
	ds_write2_b64 v167, v[130:131], v[132:133] offset1:1
	s_waitcnt vmcnt(6)
	ds_write2_b64 v193, v[134:135], v[136:137] offset1:1
	s_waitcnt vmcnt(5)
	ds_write2_b64 v198, v[138:139], v[140:141] offset1:1
	s_waitcnt vmcnt(4)
	ds_write2_b64 v199, v[142:143], v[144:145] offset1:1
	s_waitcnt vmcnt(3)
	ds_write2_b64 v201, v[170:171], v[172:173] offset1:1
	s_waitcnt vmcnt(2)
	ds_write2_b64 v217, v[194:195], v[196:197] offset1:1
	v_add_u32_e32 v130, 0x6180, v167
	s_waitcnt vmcnt(1)
	ds_write2_b64 v130, v[218:219], v[220:221] offset1:1
	v_add_u32_e32 v130, 0x71c0, v167
	s_waitcnt vmcnt(0)
	ds_write2_b64 v130, v[222:223], v[224:225] offset1:1
	s_mov_b32 s6, 0xc660000
	v_add_co_u32_e64 v130, s[6:7], s6, v208
	v_add_u32_e32 v193, 0x8200, v167
	s_nop 0
	v_addc_co_u32_e64 v131, s[6:7], 0, v209, s[6:7]
	s_mov_b32 s6, 0xc664000
	s_nop 0
	v_add_co_u32_e64 v134, s[6:7], s6, v208
	global_load_dwordx4 v[130:133], v[130:131], off
	s_nop 0
	v_addc_co_u32_e64 v135, s[6:7], 0, v209, s[6:7]
	s_mov_b32 s6, 0xc668000
	s_nop 0
	v_add_co_u32_e64 v138, s[6:7], s6, v208
	global_load_dwordx4 v[134:137], v[134:135], off
	s_nop 0
	v_addc_co_u32_e64 v139, s[6:7], 0, v209, s[6:7]
	s_mov_b32 s6, 0xc66c000
	s_nop 0
	v_add_co_u32_e64 v142, s[6:7], s6, v208
	global_load_dwordx4 v[138:141], v[138:139], off
	s_nop 0
	v_addc_co_u32_e64 v143, s[6:7], 0, v209, s[6:7]
	s_mov_b32 s6, 0xc670000
	s_nop 0
	v_add_co_u32_e64 v170, s[6:7], s6, v208
	global_load_dwordx4 v[142:145], v[142:143], off
	s_nop 0
	v_addc_co_u32_e64 v171, s[6:7], 0, v209, s[6:7]
	s_mov_b32 s6, 0xc674000
	s_nop 0
	v_add_co_u32_e64 v194, s[6:7], s6, v208
	global_load_dwordx4 v[170:173], v[170:171], off
	s_nop 0
	v_addc_co_u32_e64 v195, s[6:7], 0, v209, s[6:7]
	s_mov_b32 s6, 0xc678000
	s_nop 0
	v_add_co_u32_e64 v198, s[6:7], s6, v208
	global_load_dwordx4 v[194:197], v[194:195], off
	s_nop 0
	v_addc_co_u32_e64 v199, s[6:7], 0, v209, s[6:7]
	s_mov_b32 s6, 0xc67c000
	global_load_dwordx4 v[218:221], v[198:199], off
	v_add_co_u32_e64 v198, s[6:7], s6, v208
	s_waitcnt vmcnt(6)
	ds_write2_b64 v193, v[130:131], v[132:133] offset1:1
	v_addc_co_u32_e64 v199, s[6:7], 0, v209, s[6:7]
	global_load_dwordx4 v[222:225], v[198:199], off
	v_add_u32_e32 v130, 0x9240, v167
	s_waitcnt vmcnt(6)
	ds_write2_b64 v130, v[134:135], v[136:137] offset1:1
	v_add_u32_e32 v130, 0xa280, v167
	s_waitcnt vmcnt(5)
	ds_write2_b64 v130, v[138:139], v[140:141] offset1:1
	v_add_u32_e32 v130, 0xb2c0, v167
	s_waitcnt vmcnt(4)
	ds_write2_b64 v130, v[142:143], v[144:145] offset1:1
	v_add_u32_e32 v130, 0xc300, v167
	s_waitcnt vmcnt(3)
	ds_write2_b64 v130, v[170:171], v[172:173] offset1:1
	v_add_u32_e32 v130, 0xd340, v167
	s_waitcnt vmcnt(2)
	ds_write2_b64 v130, v[194:195], v[196:197] offset1:1
	v_add_u32_e32 v130, 0xe380, v167
	s_waitcnt vmcnt(1)
	ds_write2_b64 v130, v[218:219], v[220:221] offset1:1
	v_add_u32_e32 v130, 0xf3c0, v167
	s_waitcnt vmcnt(0)
	ds_write2_b64 v130, v[222:223], v[224:225] offset1:1
	s_waitcnt lgkmcnt(0)
	s_barrier
	v_ashrrev_i32_e32 v167, 31, v166
	v_lshl_add_u64 v[130:131], v[166:167], 1, v[210:211]
	s_mov_b64 s[6:7], 0x8640000
	v_lshl_add_u64 v[170:171], v[130:131], 0, s[6:7]
	v_add_u32_e32 v250, 0x4000, v178
	ds_read2_b64 v[194:197], v178 offset0:0 offset1:2
	ds_read2_b64 v[218:221], v250 offset0:32 offset1:34
	ds_read2_b64 v[222:225], v178 offset0:4 offset1:6
	ds_read2_b64 v[226:229], v250 offset0:36 offset1:38
	s_nop 0
	v_cvt_pk_bf16_f32 v230, v2, v3
	v_cvt_pk_bf16_f32 v231, v4, v5
	v_cvt_pk_bf16_f32 v232, v6, v7
	v_cvt_pk_bf16_f32 v233, v8, v9
	s_waitcnt lgkmcnt(2)
	s_nop 1
	v_mfma_f32_32x32x16_bf16 v[130:145], v[194:197], v[230:233], 0
	v_mfma_f32_32x32x16_bf16 v[234:249], v[218:221], v[230:233], 0
	ds_read2_b64 v[194:197], v178 offset0:8 offset1:10
	ds_read2_b64 v[218:221], v250 offset0:40 offset1:42
	s_nop 0
	v_cvt_pk_bf16_f32 v230, v10, v11
	v_cvt_pk_bf16_f32 v231, v12, v13
	v_cvt_pk_bf16_f32 v232, v14, v15
	v_cvt_pk_bf16_f32 v233, v16, v17
	s_waitcnt lgkmcnt(2)
	s_nop 1
	v_mfma_f32_32x32x16_bf16 v[130:145], v[222:225], v[230:233], v[130:145]
	v_mfma_f32_32x32x16_bf16 v[234:249], v[226:229], v[230:233], v[234:249]
	ds_read2_b64 v[222:225], v178 offset0:12 offset1:14
	ds_read2_b64 v[226:229], v250 offset0:44 offset1:46
	s_nop 0
	v_cvt_pk_bf16_f32 v230, v18, v19
	v_cvt_pk_bf16_f32 v231, v20, v21
	v_cvt_pk_bf16_f32 v232, v22, v23
	v_cvt_pk_bf16_f32 v233, v24, v25
	s_waitcnt lgkmcnt(2)
	s_nop 1
	v_mfma_f32_32x32x16_bf16 v[130:145], v[194:197], v[230:233], v[130:145]
	v_mfma_f32_32x32x16_bf16 v[234:249], v[218:221], v[230:233], v[234:249]
	ds_read2_b64 v[194:197], v178 offset0:16 offset1:18
	ds_read2_b64 v[218:221], v250 offset0:48 offset1:50
	s_nop 0
	v_cvt_pk_bf16_f32 v230, v26, v27
	v_cvt_pk_bf16_f32 v231, v28, v29
	v_cvt_pk_bf16_f32 v232, v30, v31
	v_cvt_pk_bf16_f32 v233, v32, v33
	s_waitcnt lgkmcnt(2)
	s_nop 1
	v_mfma_f32_32x32x16_bf16 v[130:145], v[222:225], v[230:233], v[130:145]
	v_mfma_f32_32x32x16_bf16 v[234:249], v[226:229], v[230:233], v[234:249]
	ds_read2_b64 v[222:225], v178 offset0:20 offset1:22
	ds_read2_b64 v[226:229], v250 offset0:52 offset1:54
	s_nop 0
	v_cvt_pk_bf16_f32 v230, v34, v35
	v_cvt_pk_bf16_f32 v231, v36, v37
	v_cvt_pk_bf16_f32 v232, v38, v39
	v_cvt_pk_bf16_f32 v233, v40, v41
	s_waitcnt lgkmcnt(2)
	s_nop 1
	v_mfma_f32_32x32x16_bf16 v[130:145], v[194:197], v[230:233], v[130:145]
	v_mfma_f32_32x32x16_bf16 v[234:249], v[218:221], v[230:233], v[234:249]
	ds_read2_b64 v[194:197], v178 offset0:24 offset1:26
	ds_read2_b64 v[218:221], v250 offset0:56 offset1:58
	s_nop 0
	v_cvt_pk_bf16_f32 v230, v42, v43
	v_cvt_pk_bf16_f32 v231, v44, v45
	v_cvt_pk_bf16_f32 v232, v46, v47
	v_cvt_pk_bf16_f32 v233, v48, v49
	s_waitcnt lgkmcnt(2)
	s_nop 1
	v_mfma_f32_32x32x16_bf16 v[130:145], v[222:225], v[230:233], v[130:145]
	v_mfma_f32_32x32x16_bf16 v[234:249], v[226:229], v[230:233], v[234:249]
	ds_read2_b64 v[222:225], v178 offset0:28 offset1:30
	ds_read2_b64 v[226:229], v250 offset0:60 offset1:62
	s_nop 0
	v_cvt_pk_bf16_f32 v230, v50, v51
	v_cvt_pk_bf16_f32 v231, v52, v53
	v_cvt_pk_bf16_f32 v232, v54, v55
	v_cvt_pk_bf16_f32 v233, v56, v57
	s_waitcnt lgkmcnt(2)
	s_nop 1
	v_mfma_f32_32x32x16_bf16 v[130:145], v[194:197], v[230:233], v[130:145]
	v_mfma_f32_32x32x16_bf16 v[234:249], v[218:221], v[230:233], v[234:249]
	ds_read2_b64 v[194:197], v178 offset0:32 offset1:34
	ds_read2_b64 v[218:221], v250 offset0:64 offset1:66
	s_nop 0
	v_cvt_pk_bf16_f32 v230, v58, v59
	v_cvt_pk_bf16_f32 v231, v60, v61
	v_cvt_pk_bf16_f32 v232, v62, v63
	v_cvt_pk_bf16_f32 v233, v64, v65
	s_waitcnt lgkmcnt(2)
	s_nop 1
	v_mfma_f32_32x32x16_bf16 v[130:145], v[222:225], v[230:233], v[130:145]
	v_mfma_f32_32x32x16_bf16 v[234:249], v[226:229], v[230:233], v[234:249]
	ds_read2_b64 v[222:225], v178 offset0:36 offset1:38
	ds_read2_b64 v[226:229], v250 offset0:68 offset1:70
	s_nop 0
	v_cvt_pk_bf16_f32 v230, v66, v67
	v_cvt_pk_bf16_f32 v231, v68, v69
	v_cvt_pk_bf16_f32 v232, v70, v71
	v_cvt_pk_bf16_f32 v233, v72, v73
	s_waitcnt lgkmcnt(2)
	s_nop 1
	v_mfma_f32_32x32x16_bf16 v[130:145], v[194:197], v[230:233], v[130:145]
	v_mfma_f32_32x32x16_bf16 v[234:249], v[218:221], v[230:233], v[234:249]
	ds_read2_b64 v[194:197], v178 offset0:40 offset1:42
	ds_read2_b64 v[218:221], v250 offset0:72 offset1:74
	s_nop 0
	v_cvt_pk_bf16_f32 v230, v74, v75
	v_cvt_pk_bf16_f32 v231, v76, v77
	v_cvt_pk_bf16_f32 v232, v78, v79
	v_cvt_pk_bf16_f32 v233, v80, v81
	s_waitcnt lgkmcnt(2)
	s_nop 1
	v_mfma_f32_32x32x16_bf16 v[130:145], v[222:225], v[230:233], v[130:145]
	v_mfma_f32_32x32x16_bf16 v[234:249], v[226:229], v[230:233], v[234:249]
	ds_read2_b64 v[222:225], v178 offset0:44 offset1:46
	ds_read2_b64 v[226:229], v250 offset0:76 offset1:78
	s_nop 0
	v_cvt_pk_bf16_f32 v230, v82, v83
	v_cvt_pk_bf16_f32 v231, v84, v85
	v_cvt_pk_bf16_f32 v232, v86, v87
	v_cvt_pk_bf16_f32 v233, v88, v89
	s_waitcnt lgkmcnt(2)
	s_nop 1
	v_mfma_f32_32x32x16_bf16 v[130:145], v[194:197], v[230:233], v[130:145]
	v_mfma_f32_32x32x16_bf16 v[234:249], v[218:221], v[230:233], v[234:249]
	ds_read2_b64 v[194:197], v178 offset0:48 offset1:50
	ds_read2_b64 v[218:221], v250 offset0:80 offset1:82
	s_nop 0
	v_cvt_pk_bf16_f32 v230, v90, v91
	v_cvt_pk_bf16_f32 v231, v92, v93
	v_cvt_pk_bf16_f32 v232, v94, v95
	v_cvt_pk_bf16_f32 v233, v96, v97
	s_waitcnt lgkmcnt(2)
	s_nop 1
	v_mfma_f32_32x32x16_bf16 v[130:145], v[222:225], v[230:233], v[130:145]
	v_mfma_f32_32x32x16_bf16 v[234:249], v[226:229], v[230:233], v[234:249]
	ds_read2_b64 v[222:225], v178 offset0:52 offset1:54
	ds_read2_b64 v[226:229], v250 offset0:84 offset1:86
	s_nop 0
	v_cvt_pk_bf16_f32 v230, v98, v99
	v_cvt_pk_bf16_f32 v231, v100, v101
	v_cvt_pk_bf16_f32 v232, v102, v103
	v_cvt_pk_bf16_f32 v233, v104, v105
	s_waitcnt lgkmcnt(2)
	s_nop 1
	v_mfma_f32_32x32x16_bf16 v[130:145], v[194:197], v[230:233], v[130:145]
	v_mfma_f32_32x32x16_bf16 v[234:249], v[218:221], v[230:233], v[234:249]
	ds_read2_b64 v[194:197], v178 offset0:56 offset1:58
	ds_read2_b64 v[218:221], v250 offset0:88 offset1:90
	s_nop 0
	v_cvt_pk_bf16_f32 v230, v106, v107
	v_cvt_pk_bf16_f32 v231, v108, v109
	v_cvt_pk_bf16_f32 v232, v110, v111
	v_cvt_pk_bf16_f32 v233, v112, v113
	s_waitcnt lgkmcnt(2)
	s_nop 1
	v_mfma_f32_32x32x16_bf16 v[130:145], v[222:225], v[230:233], v[130:145]
	v_mfma_f32_32x32x16_bf16 v[234:249], v[226:229], v[230:233], v[234:249]
	ds_read2_b64 v[222:225], v178 offset0:60 offset1:62
	ds_read2_b64 v[226:229], v250 offset0:92 offset1:94
	s_nop 0
	v_cvt_pk_bf16_f32 v230, v114, v115
	v_cvt_pk_bf16_f32 v231, v116, v117
	v_cvt_pk_bf16_f32 v232, v118, v119
	v_cvt_pk_bf16_f32 v233, v120, v121
	s_waitcnt lgkmcnt(2)
	s_nop 1
	v_mfma_f32_32x32x16_bf16 v[130:145], v[194:197], v[230:233], v[130:145]
	v_mfma_f32_32x32x16_bf16 v[234:249], v[218:221], v[230:233], v[234:249]
	s_nop 0
	v_cvt_pk_bf16_f32 v230, v122, v123
	v_cvt_pk_bf16_f32 v231, v124, v125
	v_cvt_pk_bf16_f32 v232, v126, v127
	v_cvt_pk_bf16_f32 v233, v128, v129
	s_waitcnt lgkmcnt(0)
	s_nop 1
	v_mfma_f32_32x32x16_bf16 v[130:145], v[222:225], v[230:233], v[130:145]
	v_mfma_f32_32x32x16_bf16 v[234:249], v[226:229], v[230:233], v[234:249]
	v_or_b32_e32 v172, v168, v174
	v_ashrrev_i32_e32 v173, 31, v172
	v_fma_f32 v193, 0, v192, v153
	v_exp_f32_e32 v193, v193
	v_lshlrev_b64 v[172:173], 12, v[172:173]
	v_lshl_add_u64 v[194:195], v[170:171], 0, v[172:173]
	s_nop 7
	v_mul_f32_e32 v130, v193, v130
	v_mov_b32_e32 v251, 0x7fff
	v_bfe_u32 v250, v130, 16, 1
	v_add3_u32 v130, v130, v250, v251
	global_store_short_d16_hi v[194:195], v130, off
	v_add_f32_e32 v130, v153, v192
	v_exp_f32_e32 v130, v130
	s_nop 0
	v_mul_f32_e32 v130, v130, v131
	v_bfe_u32 v250, v130, 16, 1
	v_add3_u32 v193, v130, v250, v251
	v_or_b32_e32 v130, 0x1000, v172
	v_mov_b32_e32 v131, v173
	v_lshl_add_u64 v[130:131], v[170:171], 0, v[130:131]
	global_store_short_d16_hi v[130:131], v193, off
	v_fma_f32 v130, 2.0, v192, v153
	v_exp_f32_e32 v130, v130
	v_mov_b32_e32 v131, v173
	v_mul_f32_e32 v130, v130, v132
	v_bfe_u32 v250, v130, 16, 1
	v_add3_u32 v132, v130, v250, v251
	v_or_b32_e32 v130, 0x2000, v172
	v_lshl_add_u64 v[130:131], v[170:171], 0, v[130:131]
	global_store_short_d16_hi v[130:131], v132, off
	v_fmamk_f32 v130, v192, 0x40400000, v153
	v_exp_f32_e32 v130, v130
	v_mov_b32_e32 v131, v173
	v_mul_f32_e32 v130, v130, v133
	v_bfe_u32 v250, v130, 16, 1
	v_add3_u32 v132, v130, v250, v251
	v_or_b32_e32 v130, 0x3000, v172
	v_lshl_add_u64 v[130:131], v[170:171], 0, v[130:131]
	global_store_short_d16_hi v[130:131], v132, off
	v_fmamk_f32 v130, v192, 0x41000000, v153
	v_exp_f32_e32 v130, v130
	v_mov_b32_e32 v131, v173
	v_mul_f32_e32 v130, v130, v134
	v_bfe_u32 v250, v130, 16, 1
	v_add3_u32 v132, v130, v250, v251
	v_or_b32_e32 v130, 0x8000, v172
	v_lshl_add_u64 v[130:131], v[170:171], 0, v[130:131]
	global_store_short_d16_hi v[130:131], v132, off
	v_fmamk_f32 v130, v192, 0x41100000, v153
	v_exp_f32_e32 v130, v130
	v_mov_b32_e32 v131, v173
	v_mul_f32_e32 v130, v130, v135
	v_bfe_u32 v250, v130, 16, 1
	v_add3_u32 v132, v130, v250, v251
	v_or_b32_e32 v130, 0x9000, v172
	v_lshl_add_u64 v[130:131], v[170:171], 0, v[130:131]
	global_store_short_d16_hi v[130:131], v132, off
	v_fmamk_f32 v130, v192, 0x41200000, v153
	v_exp_f32_e32 v130, v130
	v_mov_b32_e32 v131, v173
	v_mul_f32_e32 v130, v130, v136
	v_bfe_u32 v250, v130, 16, 1
	v_add3_u32 v132, v130, v250, v251
	v_or_b32_e32 v130, 0xa000, v172
	v_lshl_add_u64 v[130:131], v[170:171], 0, v[130:131]
	global_store_short_d16_hi v[130:131], v132, off
	v_fmamk_f32 v130, v192, 0x41300000, v153
	v_exp_f32_e32 v130, v130
	v_mov_b32_e32 v131, v173
	v_mul_f32_e32 v130, v130, v137
	v_bfe_u32 v250, v130, 16, 1
	v_add3_u32 v132, v130, v250, v251
	v_or_b32_e32 v130, 0xb000, v172
	v_lshl_add_u64 v[130:131], v[170:171], 0, v[130:131]
	global_store_short_d16_hi v[130:131], v132, off
	v_fmamk_f32 v130, v192, 0x41800000, v153
	v_exp_f32_e32 v130, v130
	v_mov_b32_e32 v131, v173
	v_mul_f32_e32 v130, v130, v138
	v_bfe_u32 v250, v130, 16, 1
	v_add3_u32 v132, v130, v250, v251
	v_or_b32_e32 v130, 0x10000, v172
	v_lshl_add_u64 v[130:131], v[170:171], 0, v[130:131]
	global_store_short_d16_hi v[130:131], v132, off
	v_fmamk_f32 v130, v192, 0x41880000, v153
	v_exp_f32_e32 v130, v130
	v_mov_b32_e32 v131, v173
	v_mul_f32_e32 v130, v130, v139
	v_bfe_u32 v250, v130, 16, 1
	v_add3_u32 v132, v130, v250, v251
	v_or_b32_e32 v130, 0x11000, v172
	v_lshl_add_u64 v[130:131], v[170:171], 0, v[130:131]
	global_store_short_d16_hi v[130:131], v132, off
	v_fmamk_f32 v130, v192, 0x41900000, v153
	v_exp_f32_e32 v130, v130
	v_mov_b32_e32 v131, v173
	v_mul_f32_e32 v130, v130, v140
	v_bfe_u32 v250, v130, 16, 1
	v_add3_u32 v132, v130, v250, v251
	v_or_b32_e32 v130, 0x12000, v172
	v_lshl_add_u64 v[130:131], v[170:171], 0, v[130:131]
	global_store_short_d16_hi v[130:131], v132, off
	v_fmamk_f32 v130, v192, 0x41980000, v153
	v_exp_f32_e32 v130, v130
	v_mov_b32_e32 v131, v173
	v_mul_f32_e32 v130, v130, v141
	v_bfe_u32 v250, v130, 16, 1
	v_add3_u32 v132, v130, v250, v251
	v_or_b32_e32 v130, 0x13000, v172
	v_lshl_add_u64 v[130:131], v[170:171], 0, v[130:131]
	global_store_short_d16_hi v[130:131], v132, off
	v_fmamk_f32 v130, v192, 0x41c00000, v153
	v_exp_f32_e32 v130, v130
	v_mov_b32_e32 v131, v173
	v_mul_f32_e32 v130, v130, v142
	v_bfe_u32 v250, v130, 16, 1
	v_add3_u32 v132, v130, v250, v251
	v_or_b32_e32 v130, 0x18000, v172
	v_lshl_add_u64 v[130:131], v[170:171], 0, v[130:131]
	global_store_short_d16_hi v[130:131], v132, off
	v_fmamk_f32 v130, v192, 0x41c80000, v153
	v_exp_f32_e32 v130, v130
	v_mov_b32_e32 v131, v173
	v_mul_f32_e32 v130, v130, v143
	v_bfe_u32 v250, v130, 16, 1
	v_add3_u32 v132, v130, v250, v251
	v_or_b32_e32 v130, 0x19000, v172
	v_lshl_add_u64 v[130:131], v[170:171], 0, v[130:131]
	global_store_short_d16_hi v[130:131], v132, off
	v_fmamk_f32 v130, v192, 0x41d00000, v153
	v_exp_f32_e32 v130, v130
	v_mov_b32_e32 v131, v173
	v_mul_f32_e32 v130, v130, v144
	v_bfe_u32 v250, v130, 16, 1
	v_add3_u32 v132, v130, v250, v251
	v_or_b32_e32 v130, 0x1a000, v172
	v_lshl_add_u64 v[130:131], v[170:171], 0, v[130:131]
	global_store_short_d16_hi v[130:131], v132, off
	v_fmamk_f32 v130, v192, 0x41d80000, v153
	v_exp_f32_e32 v130, v130
	v_mov_b32_e32 v131, v173
	v_mul_f32_e32 v130, v130, v145
	v_bfe_u32 v250, v130, 16, 1
	v_add3_u32 v132, v130, v250, v251
	v_or_b32_e32 v130, 0x1b000, v172
	v_lshl_add_u64 v[130:131], v[170:171], 0, v[130:131]
	global_store_short_d16_hi v[130:131], v132, off
	v_mov_b32_e32 v130, v234
	v_mov_b32_e32 v131, v235
	v_mov_b32_e32 v132, v236
	v_mov_b32_e32 v133, v237
	v_mov_b32_e32 v134, v238
	v_mov_b32_e32 v135, v239
	v_mov_b32_e32 v136, v240
	v_mov_b32_e32 v137, v241
	v_mov_b32_e32 v138, v242
	v_mov_b32_e32 v139, v243
	v_mov_b32_e32 v140, v244
	v_mov_b32_e32 v141, v245
	v_mov_b32_e32 v142, v246
	v_mov_b32_e32 v143, v247
	v_mov_b32_e32 v144, v248
	v_mov_b32_e32 v145, v249
	v_fmamk_f32 v193, v192, 0x42000000, v153
	v_exp_f32_e32 v193, v193
	v_or_b32_e32 v194, 0x20000, v172
	v_mov_b32_e32 v195, v173
	v_lshl_add_u64 v[194:195], v[170:171], 0, v[194:195]
	s_nop 6
	v_mul_f32_e32 v130, v193, v130
	v_mov_b32_e32 v251, 0x7fff
	v_bfe_u32 v250, v130, 16, 1
	v_add3_u32 v130, v130, v250, v251
	global_store_short_d16_hi v[194:195], v130, off
	v_fmamk_f32 v130, v192, 0x42040000, v153
	v_exp_f32_e32 v130, v130
	s_nop 0
	v_mul_f32_e32 v130, v130, v131
	v_bfe_u32 v250, v130, 16, 1
	v_add3_u32 v193, v130, v250, v251
	v_or_b32_e32 v130, 0x21000, v172
	v_mov_b32_e32 v131, v173
	v_lshl_add_u64 v[130:131], v[170:171], 0, v[130:131]
	global_store_short_d16_hi v[130:131], v193, off
	v_fmamk_f32 v130, v192, 0x42080000, v153
	v_exp_f32_e32 v130, v130
	v_mov_b32_e32 v131, v173
	v_mul_f32_e32 v130, v130, v132
	v_bfe_u32 v250, v130, 16, 1
	v_add3_u32 v132, v130, v250, v251
	v_or_b32_e32 v130, 0x22000, v172
	v_lshl_add_u64 v[130:131], v[170:171], 0, v[130:131]
	global_store_short_d16_hi v[130:131], v132, off
	v_fmamk_f32 v130, v192, 0x420c0000, v153
	v_exp_f32_e32 v130, v130
	v_mov_b32_e32 v131, v173
	v_mul_f32_e32 v130, v130, v133
	v_bfe_u32 v250, v130, 16, 1
	v_add3_u32 v132, v130, v250, v251
	v_or_b32_e32 v130, 0x23000, v172
	v_lshl_add_u64 v[130:131], v[170:171], 0, v[130:131]
	global_store_short_d16_hi v[130:131], v132, off
	v_fmamk_f32 v130, v192, 0x42200000, v153
	v_exp_f32_e32 v130, v130
	v_mov_b32_e32 v131, v173
	v_mul_f32_e32 v130, v130, v134
	v_bfe_u32 v250, v130, 16, 1
	v_add3_u32 v132, v130, v250, v251
	v_or_b32_e32 v130, 0x28000, v172
	v_lshl_add_u64 v[130:131], v[170:171], 0, v[130:131]
	global_store_short_d16_hi v[130:131], v132, off
	v_fmamk_f32 v130, v192, 0x42240000, v153
	v_exp_f32_e32 v130, v130
	v_mov_b32_e32 v131, v173
	v_mul_f32_e32 v130, v130, v135
	v_bfe_u32 v250, v130, 16, 1
	v_add3_u32 v132, v130, v250, v251
	v_or_b32_e32 v130, 0x29000, v172
	v_lshl_add_u64 v[130:131], v[170:171], 0, v[130:131]
	global_store_short_d16_hi v[130:131], v132, off
	v_fmamk_f32 v130, v192, 0x42280000, v153
	v_exp_f32_e32 v130, v130
	v_mov_b32_e32 v131, v173
	v_mul_f32_e32 v130, v130, v136
	v_bfe_u32 v250, v130, 16, 1
	v_add3_u32 v132, v130, v250, v251
	v_or_b32_e32 v130, 0x2a000, v172
	v_lshl_add_u64 v[130:131], v[170:171], 0, v[130:131]
	global_store_short_d16_hi v[130:131], v132, off
	v_fmamk_f32 v130, v192, 0x422c0000, v153
	v_exp_f32_e32 v130, v130
	v_mov_b32_e32 v131, v173
	v_mul_f32_e32 v130, v130, v137
	v_bfe_u32 v250, v130, 16, 1
	v_add3_u32 v132, v130, v250, v251
	v_or_b32_e32 v130, 0x2b000, v172
	v_lshl_add_u64 v[130:131], v[170:171], 0, v[130:131]
	global_store_short_d16_hi v[130:131], v132, off
	v_fmamk_f32 v130, v192, 0x42400000, v153
	v_exp_f32_e32 v130, v130
	v_mov_b32_e32 v131, v173
	v_mul_f32_e32 v130, v130, v138
	v_bfe_u32 v250, v130, 16, 1
	v_add3_u32 v132, v130, v250, v251
	v_or_b32_e32 v130, 0x30000, v172
	v_lshl_add_u64 v[130:131], v[170:171], 0, v[130:131]
	global_store_short_d16_hi v[130:131], v132, off
	v_fmamk_f32 v130, v192, 0x42440000, v153
	v_exp_f32_e32 v130, v130
	v_mov_b32_e32 v131, v173
	v_mul_f32_e32 v130, v130, v139
	v_bfe_u32 v250, v130, 16, 1
	v_add3_u32 v132, v130, v250, v251
	v_or_b32_e32 v130, 0x31000, v172
	v_lshl_add_u64 v[130:131], v[170:171], 0, v[130:131]
	global_store_short_d16_hi v[130:131], v132, off
	v_fmamk_f32 v130, v192, 0x42480000, v153
	v_exp_f32_e32 v130, v130
	v_mov_b32_e32 v131, v173
	v_mul_f32_e32 v130, v130, v140
	v_bfe_u32 v250, v130, 16, 1
	v_add3_u32 v132, v130, v250, v251
	v_or_b32_e32 v130, 0x32000, v172
	v_lshl_add_u64 v[130:131], v[170:171], 0, v[130:131]
	global_store_short_d16_hi v[130:131], v132, off
	v_fmamk_f32 v130, v192, 0x424c0000, v153
	v_exp_f32_e32 v130, v130
	v_mov_b32_e32 v131, v173
	v_mul_f32_e32 v130, v130, v141
	v_bfe_u32 v250, v130, 16, 1
	v_add3_u32 v132, v130, v250, v251
	v_or_b32_e32 v130, 0x33000, v172
	v_lshl_add_u64 v[130:131], v[170:171], 0, v[130:131]
	global_store_short_d16_hi v[130:131], v132, off
	v_fmamk_f32 v130, v192, 0x42600000, v153
	v_exp_f32_e32 v130, v130
	v_mov_b32_e32 v131, v173
	v_mul_f32_e32 v130, v130, v142
	v_bfe_u32 v250, v130, 16, 1
	v_add3_u32 v132, v130, v250, v251
	v_or_b32_e32 v130, 0x38000, v172
	v_lshl_add_u64 v[130:131], v[170:171], 0, v[130:131]
	global_store_short_d16_hi v[130:131], v132, off
	v_fmamk_f32 v130, v192, 0x42640000, v153
	v_exp_f32_e32 v130, v130
	v_mov_b32_e32 v131, v173
	v_mul_f32_e32 v130, v130, v143
	v_bfe_u32 v250, v130, 16, 1
	v_add3_u32 v132, v130, v250, v251
	v_or_b32_e32 v130, 0x39000, v172
	v_lshl_add_u64 v[130:131], v[170:171], 0, v[130:131]
	global_store_short_d16_hi v[130:131], v132, off
	v_fmamk_f32 v130, v192, 0x42680000, v153
	v_exp_f32_e32 v130, v130
	v_mov_b32_e32 v131, v173
	v_mul_f32_e32 v130, v130, v144
	v_bfe_u32 v250, v130, 16, 1
	v_add3_u32 v132, v130, v250, v251
	v_or_b32_e32 v130, 0x3a000, v172
	v_lshl_add_u64 v[130:131], v[170:171], 0, v[130:131]
	global_store_short_d16_hi v[130:131], v132, off
	v_fmamk_f32 v130, v192, 0x426c0000, v153
	v_exp_f32_e32 v130, v130
	v_mov_b32_e32 v131, v173
	v_mul_f32_e32 v130, v130, v145
	v_bfe_u32 v250, v130, 16, 1
	v_add3_u32 v132, v130, v250, v251
	v_or_b32_e32 v130, 0x3b000, v172
	v_lshl_add_u64 v[130:131], v[170:171], 0, v[130:131]
	global_store_short_d16_hi v[130:131], v132, off
	v_add_u32_e32 v250, 0xc000, v178
	v_add_u32_e32 v251, 0x8000, v178
	ds_read2_b64 v[194:197], v251 offset0:64 offset1:66
	ds_read2_b64 v[218:221], v250 offset0:96 offset1:98
	ds_read2_b64 v[222:225], v251 offset0:68 offset1:70
	ds_read2_b64 v[226:229], v250 offset0:100 offset1:102
	s_nop 0
	v_cvt_pk_bf16_f32 v230, v2, v3
	v_cvt_pk_bf16_f32 v231, v4, v5
	v_cvt_pk_bf16_f32 v232, v6, v7
	v_cvt_pk_bf16_f32 v233, v8, v9
	s_waitcnt lgkmcnt(2)
	s_nop 1
	v_mfma_f32_32x32x16_bf16 v[130:145], v[194:197], v[230:233], 0
	v_mfma_f32_32x32x16_bf16 v[234:249], v[218:221], v[230:233], 0
	ds_read2_b64 v[194:197], v251 offset0:72 offset1:74
	ds_read2_b64 v[218:221], v250 offset0:104 offset1:106
	s_nop 0
	v_cvt_pk_bf16_f32 v230, v10, v11
	v_cvt_pk_bf16_f32 v231, v12, v13
	v_cvt_pk_bf16_f32 v232, v14, v15
	v_cvt_pk_bf16_f32 v233, v16, v17
	s_waitcnt lgkmcnt(2)
	s_nop 1
	v_mfma_f32_32x32x16_bf16 v[130:145], v[222:225], v[230:233], v[130:145]
	v_mfma_f32_32x32x16_bf16 v[234:249], v[226:229], v[230:233], v[234:249]
	ds_read2_b64 v[222:225], v251 offset0:76 offset1:78
	ds_read2_b64 v[226:229], v250 offset0:108 offset1:110
	s_nop 0
	v_cvt_pk_bf16_f32 v230, v18, v19
	v_cvt_pk_bf16_f32 v231, v20, v21
	v_cvt_pk_bf16_f32 v232, v22, v23
	v_cvt_pk_bf16_f32 v233, v24, v25
	s_waitcnt lgkmcnt(2)
	s_nop 1
	v_mfma_f32_32x32x16_bf16 v[130:145], v[194:197], v[230:233], v[130:145]
	v_mfma_f32_32x32x16_bf16 v[234:249], v[218:221], v[230:233], v[234:249]
	ds_read2_b64 v[194:197], v251 offset0:80 offset1:82
	ds_read2_b64 v[218:221], v250 offset0:112 offset1:114
	s_nop 0
	v_cvt_pk_bf16_f32 v230, v26, v27
	v_cvt_pk_bf16_f32 v231, v28, v29
	v_cvt_pk_bf16_f32 v232, v30, v31
	v_cvt_pk_bf16_f32 v233, v32, v33
	s_waitcnt lgkmcnt(2)
	s_nop 1
	v_mfma_f32_32x32x16_bf16 v[130:145], v[222:225], v[230:233], v[130:145]
	v_mfma_f32_32x32x16_bf16 v[234:249], v[226:229], v[230:233], v[234:249]
	ds_read2_b64 v[222:225], v251 offset0:84 offset1:86
	ds_read2_b64 v[226:229], v250 offset0:116 offset1:118
	s_nop 0
	v_cvt_pk_bf16_f32 v230, v34, v35
	v_cvt_pk_bf16_f32 v231, v36, v37
	v_cvt_pk_bf16_f32 v232, v38, v39
	v_cvt_pk_bf16_f32 v233, v40, v41
	s_waitcnt lgkmcnt(2)
	s_nop 1
	v_mfma_f32_32x32x16_bf16 v[130:145], v[194:197], v[230:233], v[130:145]
	v_mfma_f32_32x32x16_bf16 v[234:249], v[218:221], v[230:233], v[234:249]
	ds_read2_b64 v[194:197], v251 offset0:88 offset1:90
	ds_read2_b64 v[218:221], v250 offset0:120 offset1:122
	s_nop 0
	v_cvt_pk_bf16_f32 v230, v42, v43
	v_cvt_pk_bf16_f32 v231, v44, v45
	v_cvt_pk_bf16_f32 v232, v46, v47
	v_cvt_pk_bf16_f32 v233, v48, v49
	s_waitcnt lgkmcnt(2)
	s_nop 1
	v_mfma_f32_32x32x16_bf16 v[130:145], v[222:225], v[230:233], v[130:145]
	v_mfma_f32_32x32x16_bf16 v[234:249], v[226:229], v[230:233], v[234:249]
	ds_read2_b64 v[222:225], v251 offset0:92 offset1:94
	ds_read2_b64 v[226:229], v250 offset0:124 offset1:126
	s_nop 0
	v_cvt_pk_bf16_f32 v230, v50, v51
	v_cvt_pk_bf16_f32 v231, v52, v53
	v_cvt_pk_bf16_f32 v232, v54, v55
	v_cvt_pk_bf16_f32 v233, v56, v57
	s_waitcnt lgkmcnt(2)
	s_nop 1
	v_mfma_f32_32x32x16_bf16 v[130:145], v[194:197], v[230:233], v[130:145]
	v_mfma_f32_32x32x16_bf16 v[234:249], v[218:221], v[230:233], v[234:249]
	ds_read2_b64 v[194:197], v251 offset0:96 offset1:98
	ds_read2_b64 v[218:221], v250 offset0:128 offset1:130
	s_nop 0
	v_cvt_pk_bf16_f32 v230, v58, v59
	v_cvt_pk_bf16_f32 v231, v60, v61
	v_cvt_pk_bf16_f32 v232, v62, v63
	v_cvt_pk_bf16_f32 v233, v64, v65
	s_waitcnt lgkmcnt(2)
	s_nop 1
	v_mfma_f32_32x32x16_bf16 v[130:145], v[222:225], v[230:233], v[130:145]
	v_mfma_f32_32x32x16_bf16 v[234:249], v[226:229], v[230:233], v[234:249]
	ds_read2_b64 v[222:225], v251 offset0:100 offset1:102
	ds_read2_b64 v[226:229], v250 offset0:132 offset1:134
	s_nop 0
	v_cvt_pk_bf16_f32 v230, v66, v67
	v_cvt_pk_bf16_f32 v231, v68, v69
	v_cvt_pk_bf16_f32 v232, v70, v71
	v_cvt_pk_bf16_f32 v233, v72, v73
	s_waitcnt lgkmcnt(2)
	s_nop 1
	v_mfma_f32_32x32x16_bf16 v[130:145], v[194:197], v[230:233], v[130:145]
	v_mfma_f32_32x32x16_bf16 v[234:249], v[218:221], v[230:233], v[234:249]
	ds_read2_b64 v[194:197], v251 offset0:104 offset1:106
	ds_read2_b64 v[218:221], v250 offset0:136 offset1:138
	s_nop 0
	v_cvt_pk_bf16_f32 v230, v74, v75
	v_cvt_pk_bf16_f32 v231, v76, v77
	v_cvt_pk_bf16_f32 v232, v78, v79
	v_cvt_pk_bf16_f32 v233, v80, v81
	s_waitcnt lgkmcnt(2)
	s_nop 1
	v_mfma_f32_32x32x16_bf16 v[130:145], v[222:225], v[230:233], v[130:145]
	v_mfma_f32_32x32x16_bf16 v[234:249], v[226:229], v[230:233], v[234:249]
	ds_read2_b64 v[222:225], v251 offset0:108 offset1:110
	ds_read2_b64 v[226:229], v250 offset0:140 offset1:142
	s_nop 0
	v_cvt_pk_bf16_f32 v230, v82, v83
	v_cvt_pk_bf16_f32 v231, v84, v85
	v_cvt_pk_bf16_f32 v232, v86, v87
	v_cvt_pk_bf16_f32 v233, v88, v89
	s_waitcnt lgkmcnt(2)
	s_nop 1
	v_mfma_f32_32x32x16_bf16 v[130:145], v[194:197], v[230:233], v[130:145]
	v_mfma_f32_32x32x16_bf16 v[234:249], v[218:221], v[230:233], v[234:249]
	ds_read2_b64 v[194:197], v251 offset0:112 offset1:114
	ds_read2_b64 v[218:221], v250 offset0:144 offset1:146
	s_nop 0
	v_cvt_pk_bf16_f32 v230, v90, v91
	v_cvt_pk_bf16_f32 v231, v92, v93
	v_cvt_pk_bf16_f32 v232, v94, v95
	v_cvt_pk_bf16_f32 v233, v96, v97
	s_waitcnt lgkmcnt(2)
	s_nop 1
	v_mfma_f32_32x32x16_bf16 v[130:145], v[222:225], v[230:233], v[130:145]
	v_mfma_f32_32x32x16_bf16 v[234:249], v[226:229], v[230:233], v[234:249]
	ds_read2_b64 v[222:225], v251 offset0:116 offset1:118
	ds_read2_b64 v[226:229], v250 offset0:148 offset1:150
	s_nop 0
	v_cvt_pk_bf16_f32 v230, v98, v99
	v_cvt_pk_bf16_f32 v231, v100, v101
	v_cvt_pk_bf16_f32 v232, v102, v103
	v_cvt_pk_bf16_f32 v233, v104, v105
	s_waitcnt lgkmcnt(2)
	s_nop 1
	v_mfma_f32_32x32x16_bf16 v[130:145], v[194:197], v[230:233], v[130:145]
	v_mfma_f32_32x32x16_bf16 v[234:249], v[218:221], v[230:233], v[234:249]
	ds_read2_b64 v[194:197], v251 offset0:120 offset1:122
	ds_read2_b64 v[218:221], v250 offset0:152 offset1:154
	s_nop 0
	v_cvt_pk_bf16_f32 v230, v106, v107
	v_cvt_pk_bf16_f32 v231, v108, v109
	v_cvt_pk_bf16_f32 v232, v110, v111
	v_cvt_pk_bf16_f32 v233, v112, v113
	s_waitcnt lgkmcnt(2)
	s_nop 1
	v_mfma_f32_32x32x16_bf16 v[130:145], v[222:225], v[230:233], v[130:145]
	v_mfma_f32_32x32x16_bf16 v[234:249], v[226:229], v[230:233], v[234:249]
	ds_read2_b64 v[222:225], v251 offset0:124 offset1:126
	ds_read2_b64 v[226:229], v250 offset0:156 offset1:158
	s_nop 0
	v_cvt_pk_bf16_f32 v230, v114, v115
	v_cvt_pk_bf16_f32 v231, v116, v117
	v_cvt_pk_bf16_f32 v232, v118, v119
	v_cvt_pk_bf16_f32 v233, v120, v121
	s_waitcnt lgkmcnt(2)
	s_nop 1
	v_mfma_f32_32x32x16_bf16 v[130:145], v[194:197], v[230:233], v[130:145]
	v_mfma_f32_32x32x16_bf16 v[234:249], v[218:221], v[230:233], v[234:249]
	s_nop 0
	v_cvt_pk_bf16_f32 v230, v122, v123
	v_cvt_pk_bf16_f32 v231, v124, v125
	v_cvt_pk_bf16_f32 v232, v126, v127
	v_cvt_pk_bf16_f32 v233, v128, v129
	s_waitcnt lgkmcnt(0)
	s_nop 1
	v_mfma_f32_32x32x16_bf16 v[130:145], v[222:225], v[230:233], v[130:145]
	v_mfma_f32_32x32x16_bf16 v[234:249], v[226:229], v[230:233], v[234:249]
	v_fmamk_f32 v193, v192, 0x42800000, v153
	v_exp_f32_e32 v193, v193
	v_or_b32_e32 v194, 0x40000, v172
	v_mov_b32_e32 v195, v173
	v_lshl_add_u64 v[194:195], v[170:171], 0, v[194:195]
	s_nop 6
	v_mul_f32_e32 v130, v193, v130
	v_mov_b32_e32 v251, 0x7fff
	v_bfe_u32 v250, v130, 16, 1
	v_add3_u32 v130, v130, v250, v251
	global_store_short_d16_hi v[194:195], v130, off
	v_fmamk_f32 v130, v192, 0x42820000, v153
	v_exp_f32_e32 v130, v130
	s_nop 0
	v_mul_f32_e32 v130, v130, v131
	v_bfe_u32 v250, v130, 16, 1
	v_add3_u32 v193, v130, v250, v251
	v_or_b32_e32 v130, 0x41000, v172
	v_mov_b32_e32 v131, v173
	v_lshl_add_u64 v[130:131], v[170:171], 0, v[130:131]
	global_store_short_d16_hi v[130:131], v193, off
	v_fmamk_f32 v130, v192, 0x42840000, v153
	v_exp_f32_e32 v130, v130
	v_mov_b32_e32 v131, v173
	v_mul_f32_e32 v130, v130, v132
	v_bfe_u32 v250, v130, 16, 1
	v_add3_u32 v132, v130, v250, v251
	v_or_b32_e32 v130, 0x42000, v172
	v_lshl_add_u64 v[130:131], v[170:171], 0, v[130:131]
	global_store_short_d16_hi v[130:131], v132, off
	v_fmamk_f32 v130, v192, 0x42860000, v153
	v_exp_f32_e32 v130, v130
	v_mov_b32_e32 v131, v173
	v_mul_f32_e32 v130, v130, v133
	v_bfe_u32 v250, v130, 16, 1
	v_add3_u32 v132, v130, v250, v251
	v_or_b32_e32 v130, 0x43000, v172
	v_lshl_add_u64 v[130:131], v[170:171], 0, v[130:131]
	global_store_short_d16_hi v[130:131], v132, off
	v_fmamk_f32 v130, v192, 0x42900000, v153
	v_exp_f32_e32 v130, v130
	v_mov_b32_e32 v131, v173
	v_mul_f32_e32 v130, v130, v134
	v_bfe_u32 v250, v130, 16, 1
	v_add3_u32 v132, v130, v250, v251
	v_or_b32_e32 v130, 0x48000, v172
	v_lshl_add_u64 v[130:131], v[170:171], 0, v[130:131]
	global_store_short_d16_hi v[130:131], v132, off
	v_fmamk_f32 v130, v192, 0x42920000, v153
	v_exp_f32_e32 v130, v130
	v_mov_b32_e32 v131, v173
	v_mul_f32_e32 v130, v130, v135
	v_bfe_u32 v250, v130, 16, 1
	v_add3_u32 v132, v130, v250, v251
	v_or_b32_e32 v130, 0x49000, v172
	v_lshl_add_u64 v[130:131], v[170:171], 0, v[130:131]
	global_store_short_d16_hi v[130:131], v132, off
	v_fmamk_f32 v130, v192, 0x42940000, v153
	v_exp_f32_e32 v130, v130
	v_mov_b32_e32 v131, v173
	v_mul_f32_e32 v130, v130, v136
	v_bfe_u32 v250, v130, 16, 1
	v_add3_u32 v132, v130, v250, v251
	v_or_b32_e32 v130, 0x4a000, v172
	v_lshl_add_u64 v[130:131], v[170:171], 0, v[130:131]
	global_store_short_d16_hi v[130:131], v132, off
	v_fmamk_f32 v130, v192, 0x42960000, v153
	v_exp_f32_e32 v130, v130
	v_mov_b32_e32 v131, v173
	v_mul_f32_e32 v130, v130, v137
	v_bfe_u32 v250, v130, 16, 1
	v_add3_u32 v132, v130, v250, v251
	v_or_b32_e32 v130, 0x4b000, v172
	v_lshl_add_u64 v[130:131], v[170:171], 0, v[130:131]
	global_store_short_d16_hi v[130:131], v132, off
	v_fmamk_f32 v130, v192, 0x42a00000, v153
	v_exp_f32_e32 v130, v130
	v_mov_b32_e32 v131, v173
	v_mul_f32_e32 v130, v130, v138
	v_bfe_u32 v250, v130, 16, 1
	v_add3_u32 v132, v130, v250, v251
	v_or_b32_e32 v130, 0x50000, v172
	v_lshl_add_u64 v[130:131], v[170:171], 0, v[130:131]
	global_store_short_d16_hi v[130:131], v132, off
	v_fmamk_f32 v130, v192, 0x42a20000, v153
	v_exp_f32_e32 v130, v130
	v_mov_b32_e32 v131, v173
	v_mul_f32_e32 v130, v130, v139
	v_bfe_u32 v250, v130, 16, 1
	v_add3_u32 v132, v130, v250, v251
	v_or_b32_e32 v130, 0x51000, v172
	v_lshl_add_u64 v[130:131], v[170:171], 0, v[130:131]
	global_store_short_d16_hi v[130:131], v132, off
	v_fmamk_f32 v130, v192, 0x42a40000, v153
	v_exp_f32_e32 v130, v130
	v_mov_b32_e32 v131, v173
	v_mul_f32_e32 v130, v130, v140
	v_bfe_u32 v250, v130, 16, 1
	v_add3_u32 v132, v130, v250, v251
	v_or_b32_e32 v130, 0x52000, v172
	v_lshl_add_u64 v[130:131], v[170:171], 0, v[130:131]
	global_store_short_d16_hi v[130:131], v132, off
	v_fmamk_f32 v130, v192, 0x42a60000, v153
	v_exp_f32_e32 v130, v130
	v_mov_b32_e32 v131, v173
	v_mul_f32_e32 v130, v130, v141
	v_bfe_u32 v250, v130, 16, 1
	v_add3_u32 v132, v130, v250, v251
	v_or_b32_e32 v130, 0x53000, v172
	v_lshl_add_u64 v[130:131], v[170:171], 0, v[130:131]
	global_store_short_d16_hi v[130:131], v132, off
	v_fmamk_f32 v130, v192, 0x42b00000, v153
	v_exp_f32_e32 v130, v130
	v_mov_b32_e32 v131, v173
	v_mul_f32_e32 v130, v130, v142
	v_bfe_u32 v250, v130, 16, 1
	v_add3_u32 v132, v130, v250, v251
	v_or_b32_e32 v130, 0x58000, v172
	v_lshl_add_u64 v[130:131], v[170:171], 0, v[130:131]
	global_store_short_d16_hi v[130:131], v132, off
	v_fmamk_f32 v130, v192, 0x42b20000, v153
	v_exp_f32_e32 v130, v130
	v_mov_b32_e32 v131, v173
	v_mul_f32_e32 v130, v130, v143
	v_bfe_u32 v250, v130, 16, 1
	v_add3_u32 v132, v130, v250, v251
	v_or_b32_e32 v130, 0x59000, v172
	v_lshl_add_u64 v[130:131], v[170:171], 0, v[130:131]
	global_store_short_d16_hi v[130:131], v132, off
	v_fmamk_f32 v130, v192, 0x42b40000, v153
	v_exp_f32_e32 v130, v130
	v_mov_b32_e32 v131, v173
	v_mul_f32_e32 v130, v130, v144
	v_bfe_u32 v250, v130, 16, 1
	v_add3_u32 v132, v130, v250, v251
	v_or_b32_e32 v130, 0x5a000, v172
	v_lshl_add_u64 v[130:131], v[170:171], 0, v[130:131]
	global_store_short_d16_hi v[130:131], v132, off
	v_fmamk_f32 v130, v192, 0x42b60000, v153
	v_exp_f32_e32 v130, v130
	v_mov_b32_e32 v131, v173
	v_mul_f32_e32 v130, v130, v145
	v_bfe_u32 v250, v130, 16, 1
	v_add3_u32 v132, v130, v250, v251
	v_or_b32_e32 v130, 0x5b000, v172
	v_lshl_add_u64 v[130:131], v[170:171], 0, v[130:131]
	global_store_short_d16_hi v[130:131], v132, off
	v_mov_b32_e32 v130, v234
	v_mov_b32_e32 v131, v235
	v_mov_b32_e32 v132, v236
	v_mov_b32_e32 v133, v237
	v_mov_b32_e32 v134, v238
	v_mov_b32_e32 v135, v239
	v_mov_b32_e32 v136, v240
	v_mov_b32_e32 v137, v241
	v_mov_b32_e32 v138, v242
	v_mov_b32_e32 v139, v243
	v_mov_b32_e32 v140, v244
	v_mov_b32_e32 v141, v245
	v_mov_b32_e32 v142, v246
	v_mov_b32_e32 v143, v247
	v_mov_b32_e32 v144, v248
	v_mov_b32_e32 v145, v249
	v_fmamk_f32 v193, v192, 0x42c00000, v153
	v_exp_f32_e32 v193, v193
	v_or_b32_e32 v194, 0x60000, v172
	v_mov_b32_e32 v195, v173
	v_lshl_add_u64 v[194:195], v[170:171], 0, v[194:195]
	s_nop 6
	v_mul_f32_e32 v130, v193, v130
	v_mov_b32_e32 v251, 0x7fff
	v_bfe_u32 v250, v130, 16, 1
	v_add3_u32 v130, v130, v250, v251
	global_store_short_d16_hi v[194:195], v130, off
	v_fmamk_f32 v130, v192, 0x42c20000, v153
	v_exp_f32_e32 v130, v130
	s_nop 0
	v_mul_f32_e32 v130, v130, v131
	v_bfe_u32 v250, v130, 16, 1
	v_add3_u32 v193, v130, v250, v251
	v_or_b32_e32 v130, 0x61000, v172
	v_mov_b32_e32 v131, v173
	v_lshl_add_u64 v[130:131], v[170:171], 0, v[130:131]
	global_store_short_d16_hi v[130:131], v193, off
	v_fmamk_f32 v130, v192, 0x42c40000, v153
	v_exp_f32_e32 v130, v130
	v_mov_b32_e32 v131, v173
	v_mul_f32_e32 v130, v130, v132
	v_bfe_u32 v250, v130, 16, 1
	v_add3_u32 v132, v130, v250, v251
	v_or_b32_e32 v130, 0x62000, v172
	v_lshl_add_u64 v[130:131], v[170:171], 0, v[130:131]
	global_store_short_d16_hi v[130:131], v132, off
	v_fmamk_f32 v130, v192, 0x42c60000, v153
	v_exp_f32_e32 v130, v130
	v_mov_b32_e32 v131, v173
	v_mul_f32_e32 v130, v130, v133
	v_bfe_u32 v250, v130, 16, 1
	v_add3_u32 v132, v130, v250, v251
	v_or_b32_e32 v130, 0x63000, v172
	v_lshl_add_u64 v[130:131], v[170:171], 0, v[130:131]
	global_store_short_d16_hi v[130:131], v132, off
	v_fmamk_f32 v130, v192, 0x42d00000, v153
	v_exp_f32_e32 v130, v130
	v_mov_b32_e32 v131, v173
	v_mul_f32_e32 v130, v130, v134
	v_bfe_u32 v250, v130, 16, 1
	v_add3_u32 v132, v130, v250, v251
	v_or_b32_e32 v130, 0x68000, v172
	v_lshl_add_u64 v[130:131], v[170:171], 0, v[130:131]
	global_store_short_d16_hi v[130:131], v132, off
	v_fmamk_f32 v130, v192, 0x42d20000, v153
	v_exp_f32_e32 v130, v130
	v_mov_b32_e32 v131, v173
	v_mul_f32_e32 v130, v130, v135
	v_bfe_u32 v250, v130, 16, 1
	v_add3_u32 v132, v130, v250, v251
	v_or_b32_e32 v130, 0x69000, v172
	v_lshl_add_u64 v[130:131], v[170:171], 0, v[130:131]
	global_store_short_d16_hi v[130:131], v132, off
	v_fmamk_f32 v130, v192, 0x42d40000, v153
	v_exp_f32_e32 v130, v130
	v_mov_b32_e32 v131, v173
	v_mul_f32_e32 v130, v130, v136
	v_bfe_u32 v250, v130, 16, 1
	v_add3_u32 v132, v130, v250, v251
	v_or_b32_e32 v130, 0x6a000, v172
	v_lshl_add_u64 v[130:131], v[170:171], 0, v[130:131]
	global_store_short_d16_hi v[130:131], v132, off
	v_fmamk_f32 v130, v192, 0x42d60000, v153
	v_exp_f32_e32 v130, v130
	v_mov_b32_e32 v131, v173
	v_mul_f32_e32 v130, v130, v137
	v_bfe_u32 v250, v130, 16, 1
	v_add3_u32 v132, v130, v250, v251
	v_or_b32_e32 v130, 0x6b000, v172
	v_lshl_add_u64 v[130:131], v[170:171], 0, v[130:131]
	global_store_short_d16_hi v[130:131], v132, off
	v_fmamk_f32 v130, v192, 0x42e00000, v153
	v_exp_f32_e32 v130, v130
	v_mov_b32_e32 v131, v173
	v_mul_f32_e32 v130, v130, v138
	v_bfe_u32 v250, v130, 16, 1
	v_add3_u32 v132, v130, v250, v251
	v_or_b32_e32 v130, 0x70000, v172
	v_lshl_add_u64 v[130:131], v[170:171], 0, v[130:131]
	global_store_short_d16_hi v[130:131], v132, off
	v_fmamk_f32 v130, v192, 0x42e20000, v153
	v_exp_f32_e32 v130, v130
	v_mov_b32_e32 v131, v173
	v_mul_f32_e32 v130, v130, v139
	v_bfe_u32 v250, v130, 16, 1
	v_add3_u32 v132, v130, v250, v251
	v_or_b32_e32 v130, 0x71000, v172
	v_lshl_add_u64 v[130:131], v[170:171], 0, v[130:131]
	global_store_short_d16_hi v[130:131], v132, off
	v_fmamk_f32 v130, v192, 0x42e40000, v153
	v_exp_f32_e32 v130, v130
	v_mov_b32_e32 v131, v173
	v_mul_f32_e32 v130, v130, v140
	v_bfe_u32 v250, v130, 16, 1
	v_add3_u32 v132, v130, v250, v251
	v_or_b32_e32 v130, 0x72000, v172
	v_lshl_add_u64 v[130:131], v[170:171], 0, v[130:131]
	global_store_short_d16_hi v[130:131], v132, off
	v_fmamk_f32 v130, v192, 0x42e60000, v153
	v_exp_f32_e32 v130, v130
	v_mov_b32_e32 v131, v173
	v_mul_f32_e32 v130, v130, v141
	v_bfe_u32 v250, v130, 16, 1
	v_add3_u32 v132, v130, v250, v251
	v_or_b32_e32 v130, 0x73000, v172
	v_lshl_add_u64 v[130:131], v[170:171], 0, v[130:131]
	global_store_short_d16_hi v[130:131], v132, off
	v_fmamk_f32 v130, v192, 0x42f00000, v153
	v_exp_f32_e32 v130, v130
	v_mov_b32_e32 v131, v173
	v_mul_f32_e32 v130, v130, v142
	v_bfe_u32 v250, v130, 16, 1
	v_add3_u32 v132, v130, v250, v251
	v_or_b32_e32 v130, 0x78000, v172
	v_lshl_add_u64 v[130:131], v[170:171], 0, v[130:131]
	global_store_short_d16_hi v[130:131], v132, off
	v_fmamk_f32 v130, v192, 0x42f20000, v153
	v_exp_f32_e32 v130, v130
	v_mov_b32_e32 v131, v173
	v_mul_f32_e32 v130, v130, v143
	v_bfe_u32 v250, v130, 16, 1
	v_add3_u32 v132, v130, v250, v251
	v_or_b32_e32 v130, 0x79000, v172
	v_lshl_add_u64 v[130:131], v[170:171], 0, v[130:131]
	global_store_short_d16_hi v[130:131], v132, off
	v_fmamk_f32 v130, v192, 0x42f40000, v153
	v_exp_f32_e32 v130, v130
	v_mov_b32_e32 v131, v173
	v_fmac_f32_e32 v153, 0x42f60000, v192
	v_mul_f32_e32 v130, v130, v144
	v_bfe_u32 v250, v130, 16, 1
	v_add3_u32 v132, v130, v250, v251
	v_or_b32_e32 v130, 0x7a000, v172
	v_lshl_add_u64 v[130:131], v[170:171], 0, v[130:131]
	global_store_short_d16_hi v[130:131], v132, off
	v_exp_f32_e32 v130, v153
	v_or_b32_e32 v172, 0x7b000, v172
	v_mul_f32_e32 v130, v130, v145
	v_bfe_u32 v250, v130, 16, 1
	v_add3_u32 v132, v130, v250, v251
	v_lshl_add_u64 v[130:131], v[170:171], 0, v[172:173]
	global_store_short_d16_hi v[130:131], v132, off
	v_mov_b32_e32 v153, v189
	s_waitcnt vmcnt(63) expcnt(7) lgkmcnt(15)
	s_barrier
	v_lshl_add_u64 v[132:133], s[64:65], 0, v[164:165]
	v_lshlrev_b64 v[130:131], 1, v[168:169]
	v_lshl_add_u64 v[132:133], v[132:133], 0, v[130:131]
	v_lshlrev_b32_e32 v134, 4, v153
	v_and_b32_e32 v144, 0xf0, v134
	v_mov_b32_e32 v145, v1
	v_lshlrev_b32_e32 v134, 10, v153
	v_lshl_add_u64 v[132:133], v[132:133], 0, v[144:145]
	v_and_b32_e32 v134, 0x3c000, v134
	v_mov_b32_e32 v135, v1
	v_lshl_add_u64 v[172:173], v[132:133], 0, v[134:135]
	s_mov_b32 s6, 0xe640000
	v_add_co_u32_e64 v132, s[6:7], s6, v172
	v_bfe_u32 v145, v153, 4, 4
	s_nop 0
	v_addc_co_u32_e64 v133, s[6:7], 0, v173, s[6:7]
	s_mov_b32 s6, 0xe680000
	s_nop 0
	v_add_co_u32_e64 v136, s[6:7], s6, v172
	global_load_dwordx4 v[132:135], v[132:133], off
	s_nop 0
	v_addc_co_u32_e64 v137, s[6:7], 0, v173, s[6:7]
	s_mov_b32 s6, 0xe6c0000
	s_nop 0
	v_add_co_u32_e64 v140, s[6:7], s6, v172
	global_load_dwordx4 v[136:139], v[136:137], off
	s_nop 0
	v_addc_co_u32_e64 v141, s[6:7], 0, v173, s[6:7]
	s_mov_b32 s6, 0xe700000
	s_nop 0
	v_add_co_u32_e64 v168, s[6:7], s6, v172
	global_load_dwordx4 v[140:143], v[140:141], off
	s_nop 0
	v_addc_co_u32_e64 v169, s[6:7], 0, v173, s[6:7]
	s_mov_b32 s6, 0xe740000
	s_nop 0
	v_add_co_u32_e64 v192, s[6:7], s6, v172
	global_load_dwordx4 v[168:171], v[168:169], off
	s_nop 0
	v_addc_co_u32_e64 v193, s[6:7], 0, v173, s[6:7]
	s_mov_b32 s6, 0xe780000
	s_nop 0
	v_add_co_u32_e64 v196, s[6:7], s6, v172
	global_load_dwordx4 v[192:195], v[192:193], off
	s_nop 0
	v_addc_co_u32_e64 v197, s[6:7], 0, v173, s[6:7]
	s_mov_b32 s6, 0xe7c0000
	s_nop 0
	v_add_co_u32_e64 v208, s[6:7], s6, v172
	global_load_dwordx4 v[196:199], v[196:197], off
	s_nop 0
	v_addc_co_u32_e64 v209, s[6:7], 0, v173, s[6:7]
	s_mov_b32 s6, 0xe800000
	global_load_dwordx4 v[218:221], v[208:209], off
	v_add_co_u32_e64 v208, s[6:7], s6, v172
	v_mul_u32_u24_e32 v145, 0x108, v145
	s_nop 0
	v_addc_co_u32_e64 v209, s[6:7], 0, v173, s[6:7]
	global_load_dwordx4 v[222:225], v[208:209], off
	v_add3_u32 v153, v149, v144, v145
	s_waitcnt vmcnt(7)
	ds_write2_b64 v153, v[132:133], v[134:135] offset1:1
	v_add_u32_e32 v132, 0x1080, v153
	s_waitcnt vmcnt(6)
	ds_write2_b64 v132, v[136:137], v[138:139] offset1:1
	v_add_u32_e32 v132, 0x2100, v153
	s_waitcnt vmcnt(5)
	ds_write2_b64 v132, v[140:141], v[142:143] offset1:1
	v_add_u32_e32 v132, 0x3180, v153
	s_waitcnt vmcnt(4)
	ds_write2_b64 v132, v[168:169], v[170:171] offset1:1
	v_add_u32_e32 v132, 0x4200, v153
	s_waitcnt vmcnt(3)
	ds_write2_b64 v132, v[192:193], v[194:195] offset1:1
	v_add_u32_e32 v132, 0x5280, v153
	s_waitcnt vmcnt(2)
	ds_write2_b64 v132, v[196:197], v[198:199] offset1:1
	v_add_u32_e32 v132, 0x6300, v153
	s_waitcnt vmcnt(1)
	ds_write2_b64 v132, v[218:219], v[220:221] offset1:1
	v_add_u32_e32 v132, 0x7380, v153
	s_waitcnt vmcnt(0)
	ds_write2_b64 v132, v[222:223], v[224:225] offset1:1
	s_mov_b32 s6, 0xe840000
	v_add_co_u32_e64 v132, s[6:7], s6, v172
	s_nop 1
	v_addc_co_u32_e64 v133, s[6:7], 0, v173, s[6:7]
	s_mov_b32 s6, 0xe880000
	s_nop 0
	v_add_co_u32_e64 v136, s[6:7], s6, v172
	global_load_dwordx4 v[132:135], v[132:133], off
	s_nop 0
	v_addc_co_u32_e64 v137, s[6:7], 0, v173, s[6:7]
	s_mov_b32 s6, 0xe8c0000
	s_nop 0
	v_add_co_u32_e64 v140, s[6:7], s6, v172
	global_load_dwordx4 v[136:139], v[136:137], off
	s_nop 0
	v_addc_co_u32_e64 v141, s[6:7], 0, v173, s[6:7]
	s_mov_b32 s6, 0xe900000
	s_nop 0
	v_add_co_u32_e64 v144, s[6:7], s6, v172
	global_load_dwordx4 v[140:143], v[140:141], off
	s_nop 0
	v_addc_co_u32_e64 v145, s[6:7], 0, v173, s[6:7]
	s_mov_b32 s6, 0xe940000
	global_load_dwordx4 v[168:171], v[144:145], off
	v_add_co_u32_e64 v144, s[6:7], s6, v172
	s_nop 1
	v_addc_co_u32_e64 v145, s[6:7], 0, v173, s[6:7]
	s_mov_b32 s6, 0xe980000
	global_load_dwordx4 v[192:195], v[144:145], off
	v_add_co_u32_e64 v144, s[6:7], s6, v172
	s_nop 1
	v_addc_co_u32_e64 v145, s[6:7], 0, v173, s[6:7]
	s_mov_b32 s6, 0xe9c0000
	global_load_dwordx4 v[196:199], v[144:145], off
	v_add_co_u32_e64 v144, s[6:7], s6, v172
	s_nop 1
	v_addc_co_u32_e64 v145, s[6:7], 0, v173, s[6:7]
	s_mov_b32 s6, 0xea00000
	global_load_dwordx4 v[218:221], v[144:145], off
	v_add_co_u32_e64 v144, s[6:7], s6, v172
	s_nop 1
	v_addc_co_u32_e64 v145, s[6:7], 0, v173, s[6:7]
	global_load_dwordx4 v[222:225], v[144:145], off
	v_add_u32_e32 v144, 0x8400, v153
	s_waitcnt vmcnt(7)
	ds_write2_b64 v144, v[132:133], v[134:135] offset1:1
	v_add_u32_e32 v132, 0x9480, v153
	s_waitcnt vmcnt(6)
	ds_write2_b64 v132, v[136:137], v[138:139] offset1:1
	v_add_u32_e32 v132, 0xa500, v153
	s_waitcnt vmcnt(5)
	ds_write2_b64 v132, v[140:141], v[142:143] offset1:1
	v_add_u32_e32 v132, 0xb580, v153
	s_waitcnt vmcnt(4)
	ds_write2_b64 v132, v[168:169], v[170:171] offset1:1
	v_add_u32_e32 v132, 0xc600, v153
	s_waitcnt vmcnt(3)
	ds_write2_b64 v132, v[192:193], v[194:195] offset1:1
	v_add_u32_e32 v132, 0xd680, v153
	s_waitcnt vmcnt(2)
	ds_write2_b64 v132, v[196:197], v[198:199] offset1:1
	v_add_u32_e32 v132, 0xe700, v153
	s_waitcnt vmcnt(1)
	ds_write2_b64 v132, v[218:219], v[220:221] offset1:1
	v_add_u32_e32 v132, 0xf780, v153
	s_waitcnt vmcnt(0)
	ds_write2_b64 v132, v[222:223], v[224:225] offset1:1
	s_waitcnt lgkmcnt(0)
	s_barrier
	v_lshlrev_b64 v[132:133], 14, v[166:167]
	v_lshl_add_u64 v[132:133], s[64:65], 0, v[132:133]
	v_lshl_add_u64 v[130:131], v[132:133], 0, v[130:131]
	v_mov_b32_e32 v153, v1
	v_lshl_add_u64 v[134:135], v[130:131], 0, v[152:153]
	s_mov_b32 s6, 0xf640000
	v_add_co_u32_e64 v130, s[6:7], s6, v134
	v_mul_f32 v2, v2, v159
	v_mul_f32 v3, v3, v159
	v_mul_f32 v4, v4, v159
	v_mul_f32 v5, v5, v159
	s_nop 1
	v_addc_co_u32_e64 v131, s[6:7], 0, v135, s[6:7]
	v_mul_f32 v6, v6, v159
	v_mul_f32 v7, v7, v159
	v_mul_f32 v8, v8, v159
	v_mul_f32 v9, v9, v159
	v_mul_f32 v10, v10, v159
	v_mul_f32 v11, v11, v159
	v_mul_f32 v12, v12, v159
	v_mul_f32 v13, v13, v159
	v_mul_f32 v14, v14, v159
	v_mul_f32 v15, v15, v159
	v_mul_f32 v16, v16, v159
	v_mul_f32 v17, v17, v159
	v_mul_f32 v18, v18, v159
	v_mul_f32 v19, v19, v159
	v_mul_f32 v20, v20, v159
	v_mul_f32 v21, v21, v159
	v_mul_f32 v22, v22, v159
	v_mul_f32 v23, v23, v159
	v_mul_f32 v24, v24, v159
	v_mul_f32 v25, v25, v159
	v_mul_f32 v26, v26, v159
	v_mul_f32 v27, v27, v159
	v_mul_f32 v28, v28, v159
	v_mul_f32 v29, v29, v159
	v_mul_f32 v30, v30, v159
	v_mul_f32 v31, v31, v159
	v_mul_f32 v32, v32, v159
	v_mul_f32 v33, v33, v159
	v_mul_f32 v34, v34, v159
	v_mul_f32 v35, v35, v159
	v_mul_f32 v36, v36, v159
	v_mul_f32 v37, v37, v159
	v_mul_f32 v38, v38, v159
	v_mul_f32 v39, v39, v159
	v_mul_f32 v40, v40, v159
	v_mul_f32 v41, v41, v159
	v_mul_f32 v42, v42, v159
	v_mul_f32 v43, v43, v159
	v_mul_f32 v44, v44, v159
	v_mul_f32 v45, v45, v159
	v_mul_f32 v46, v46, v159
	v_mul_f32 v47, v47, v159
	v_mul_f32 v48, v48, v159
	v_mul_f32 v49, v49, v159
	v_mul_f32 v50, v50, v159
	v_mul_f32 v51, v51, v159
	v_mul_f32 v52, v52, v159
	v_mul_f32 v53, v53, v159
	v_mul_f32 v54, v54, v159
	v_mul_f32 v55, v55, v159
	v_mul_f32 v56, v56, v159
	v_mul_f32 v57, v57, v159
	v_mul_f32 v58, v58, v159
	v_mul_f32 v59, v59, v159
	v_mul_f32 v60, v60, v159
	v_mul_f32 v61, v61, v159
	v_mul_f32 v62, v62, v159
	v_mul_f32 v63, v63, v159
	v_mul_f32 v64, v64, v159
	v_mul_f32 v65, v65, v159
	v_mul_f32 v66, v66, v159
	v_mul_f32 v67, v67, v159
	v_mul_f32 v68, v68, v159
	v_mul_f32 v69, v69, v159
	v_mul_f32 v70, v70, v159
	v_mul_f32 v71, v71, v159
	v_mul_f32 v72, v72, v159
	v_mul_f32 v73, v73, v159
	v_mul_f32 v74, v74, v159
	v_mul_f32 v75, v75, v159
	v_mul_f32 v76, v76, v159
	v_mul_f32 v77, v77, v159
	v_mul_f32 v78, v78, v159
	v_mul_f32 v79, v79, v159
	v_mul_f32 v80, v80, v159
	v_mul_f32 v81, v81, v159
	v_mul_f32 v82, v82, v159
	v_mul_f32 v83, v83, v159
	v_mul_f32 v84, v84, v159
	v_mul_f32 v85, v85, v159
	v_mul_f32 v86, v86, v159
	v_mul_f32 v87, v87, v159
	v_mul_f32 v88, v88, v159
	v_mul_f32 v89, v89, v159
	v_mul_f32 v90, v90, v159
	v_mul_f32 v91, v91, v159
	v_mul_f32 v92, v92, v159
	v_mul_f32 v93, v93, v159
	v_mul_f32 v94, v94, v159
	v_mul_f32 v95, v95, v159
	v_mul_f32 v96, v96, v159
	v_mul_f32 v97, v97, v159
	v_mul_f32 v98, v98, v159
	v_mul_f32 v99, v99, v159
	v_mul_f32 v100, v100, v159
	v_mul_f32 v101, v101, v159
	v_mul_f32 v102, v102, v159
	v_mul_f32 v103, v103, v159
	v_mul_f32 v104, v104, v159
	v_mul_f32 v105, v105, v159
	v_mul_f32 v106, v106, v159
	v_mul_f32 v107, v107, v159
	v_mul_f32 v108, v108, v159
	v_mul_f32 v109, v109, v159
	v_mul_f32 v110, v110, v159
	v_mul_f32 v111, v111, v159
	v_mul_f32 v112, v112, v159
	v_mul_f32 v113, v113, v159
	v_mul_f32 v114, v114, v159
	v_mul_f32 v115, v115, v159
	v_mul_f32 v116, v116, v159
	v_mul_f32 v117, v117, v159
	v_mul_f32 v118, v118, v159
	v_mul_f32 v119, v119, v159
	v_mul_f32 v120, v120, v159
	v_mul_f32 v121, v121, v159
	v_mul_f32 v122, v122, v159
	v_mul_f32 v123, v123, v159
	v_mul_f32 v124, v124, v159
	v_mul_f32 v125, v125, v159
	v_mul_f32 v126, v126, v159
	v_mul_f32 v127, v127, v159
	v_mul_f32 v128, v128, v159
	v_mul_f32 v129, v129, v159
	global_load_dwordx4 v[130:133], v[130:131], off
	s_mov_b64 s[6:7], 0xf640000
	v_lshl_add_u64 v[142:143], v[134:135], 0, s[6:7]
	global_load_dwordx4 v[134:137], v[142:143], off offset:32
	global_load_dwordx4 v[138:141], v[142:143], off offset:64
	global_load_dwordx4 v[166:169], v[142:143], off offset:96
	global_load_dwordx4 v[234:237], v[142:143], off offset:128
	global_load_dwordx4 v[238:241], v[142:143], off offset:160
	global_load_dwordx4 v[242:245], v[142:143], off offset:192
	global_load_dwordx4 v[246:249], v[142:143], off offset:224
	v_fma_f32 v144, 0, v191, v190
	v_add_f32_e32 v145, v190, v191
	v_exp_f32_e32 v144, v144
	v_exp_f32_e32 v145, v145
	v_fmamk_f32 v153, v191, 0x42480000, v190
	s_waitcnt vmcnt(7)
	v_lshlrev_b32_e32 v170, 16, v130
	v_and_b32_e32 v171, 0xffff0000, v130
	v_fma_f32 v130, 2.0, v191, v190
	v_pk_mul_f32 v[144:145], v[144:145], v[170:171]
	v_exp_f32_e32 v170, v130
	v_fmamk_f32 v130, v191, 0x40400000, v190
	v_exp_f32_e32 v171, v130
	v_cvt_pk_bf16_f32 v130, v144, v145
	v_lshlrev_b32_e32 v144, 16, v131
	v_and_b32_e32 v145, 0xffff0000, v131
	v_fma_f32 v131, 4.0, v191, v190
	v_pk_mul_f32 v[144:145], v[170:171], v[144:145]
	v_exp_f32_e32 v170, v131
	v_fmamk_f32 v131, v191, 0x40a00000, v190
	v_exp_f32_e32 v171, v131
	v_cvt_pk_bf16_f32 v131, v144, v145
	v_lshlrev_b32_e32 v144, 16, v132
	v_and_b32_e32 v145, 0xffff0000, v132
	v_fmamk_f32 v132, v191, 0x40c00000, v190
	v_pk_mul_f32 v[144:145], v[170:171], v[144:145]
	v_exp_f32_e32 v170, v132
	v_fmamk_f32 v132, v191, 0x40e00000, v190
	v_exp_f32_e32 v171, v132
	v_cvt_pk_bf16_f32 v132, v144, v145
	v_lshlrev_b32_e32 v144, 16, v133
	v_and_b32_e32 v145, 0xffff0000, v133
	v_fmamk_f32 v133, v191, 0x41800000, v190
	v_pk_mul_f32 v[144:145], v[170:171], v[144:145]
	v_exp_f32_e32 v170, v133
	v_fmamk_f32 v133, v191, 0x41880000, v190
	v_exp_f32_e32 v171, v133
	v_cvt_pk_bf16_f32 v133, v144, v145
	s_waitcnt vmcnt(6)
	v_lshlrev_b32_e32 v144, 16, v134
	v_and_b32_e32 v145, 0xffff0000, v134
	v_fmamk_f32 v134, v191, 0x41900000, v190
	v_pk_mul_f32 v[144:145], v[170:171], v[144:145]
	v_exp_f32_e32 v170, v134
	v_fmamk_f32 v134, v191, 0x41980000, v190
	v_exp_f32_e32 v171, v134
	v_cvt_pk_bf16_f32 v134, v144, v145
	v_lshlrev_b32_e32 v144, 16, v135
	v_and_b32_e32 v145, 0xffff0000, v135
	v_fmamk_f32 v135, v191, 0x41a00000, v190
	v_pk_mul_f32 v[144:145], v[170:171], v[144:145]
	v_exp_f32_e32 v170, v135
	v_fmamk_f32 v135, v191, 0x41a80000, v190
	v_exp_f32_e32 v171, v135
	v_cvt_pk_bf16_f32 v135, v144, v145
	v_lshlrev_b32_e32 v144, 16, v136
	v_and_b32_e32 v145, 0xffff0000, v136
	v_fmamk_f32 v136, v191, 0x41b00000, v190
	v_pk_mul_f32 v[144:145], v[170:171], v[144:145]
	v_exp_f32_e32 v170, v136
	v_fmamk_f32 v136, v191, 0x41b80000, v190
	v_exp_f32_e32 v171, v136
	v_cvt_pk_bf16_f32 v136, v144, v145
	v_lshlrev_b32_e32 v144, 16, v137
	v_and_b32_e32 v145, 0xffff0000, v137
	v_fmamk_f32 v137, v191, 0x42000000, v190
	v_pk_mul_f32 v[144:145], v[170:171], v[144:145]
	v_exp_f32_e32 v170, v137
	v_fmamk_f32 v137, v191, 0x42040000, v190
	v_exp_f32_e32 v171, v137
	v_cvt_pk_bf16_f32 v137, v144, v145
	s_waitcnt vmcnt(5)
	v_lshlrev_b32_e32 v144, 16, v138
	v_and_b32_e32 v145, 0xffff0000, v138
	v_fmamk_f32 v138, v191, 0x42080000, v190
	v_pk_mul_f32 v[144:145], v[170:171], v[144:145]
	v_exp_f32_e32 v170, v138
	v_fmamk_f32 v138, v191, 0x420c0000, v190
	v_exp_f32_e32 v171, v138
	v_cvt_pk_bf16_f32 v138, v144, v145
	v_lshlrev_b32_e32 v144, 16, v139
	v_and_b32_e32 v145, 0xffff0000, v139
	v_fmamk_f32 v139, v191, 0x42100000, v190
	v_pk_mul_f32 v[144:145], v[170:171], v[144:145]
	v_exp_f32_e32 v170, v139
	v_fmamk_f32 v139, v191, 0x42140000, v190
	v_exp_f32_e32 v171, v139
	v_cvt_pk_bf16_f32 v139, v144, v145
	v_lshlrev_b32_e32 v144, 16, v140
	v_and_b32_e32 v145, 0xffff0000, v140
	v_fmamk_f32 v140, v191, 0x42180000, v190
	v_pk_mul_f32 v[144:145], v[170:171], v[144:145]
	v_exp_f32_e32 v170, v140
	v_fmamk_f32 v140, v191, 0x421c0000, v190
	v_exp_f32_e32 v171, v140
	v_cvt_pk_bf16_f32 v140, v144, v145
	v_lshlrev_b32_e32 v144, 16, v141
	v_and_b32_e32 v145, 0xffff0000, v141
	v_fmamk_f32 v141, v191, 0x42400000, v190
	v_pk_mul_f32 v[144:145], v[170:171], v[144:145]
	v_exp_f32_e32 v170, v141
	v_fmamk_f32 v141, v191, 0x42440000, v190
	v_exp_f32_e32 v171, v141
	v_cvt_pk_bf16_f32 v141, v144, v145
	s_waitcnt vmcnt(4)
	v_lshlrev_b32_e32 v144, 16, v166
	v_and_b32_e32 v145, 0xffff0000, v166
	v_pk_mul_f32 v[144:145], v[170:171], v[144:145]
	v_exp_f32_e32 v170, v153
	v_fmamk_f32 v153, v191, 0x424c0000, v190
	v_exp_f32_e32 v171, v153
	v_cvt_pk_bf16_f32 v166, v144, v145
	v_lshlrev_b32_e32 v144, 16, v167
	v_and_b32_e32 v145, 0xffff0000, v167
	v_fmamk_f32 v153, v191, 0x42500000, v190
	v_pk_mul_f32 v[144:145], v[170:171], v[144:145]
	v_exp_f32_e32 v170, v153
	v_fmamk_f32 v153, v191, 0x42540000, v190
	v_exp_f32_e32 v171, v153
	v_cvt_pk_bf16_f32 v167, v144, v145
	v_lshlrev_b32_e32 v144, 16, v168
	v_and_b32_e32 v145, 0xffff0000, v168
	v_fmamk_f32 v153, v191, 0x42580000, v190
	v_pk_mul_f32 v[144:145], v[170:171], v[144:145]
	v_exp_f32_e32 v170, v153
	v_fmamk_f32 v153, v191, 0x425c0000, v190
	v_exp_f32_e32 v171, v153
	v_cvt_pk_bf16_f32 v168, v144, v145
	v_lshlrev_b32_e32 v144, 16, v169
	v_and_b32_e32 v145, 0xffff0000, v169
	v_pk_mul_f32 v[144:145], v[170:171], v[144:145]
	s_nop 0
	v_cvt_pk_bf16_f32 v169, v144, v145
	ds_read2_b64 v[170:173], v179 offset1:1
	ds_read2_b64 v[192:195], v179 offset0:4 offset1:5
	ds_read2_b64 v[196:199], v179 offset0:8 offset1:9
	ds_read2_b64 v[218:221], v179 offset0:12 offset1:13
	s_waitcnt lgkmcnt(3)
	v_mfma_f32_32x32x16_bf16 v[2:17], v[170:173], v[130:133], v[2:17]
	v_add_u32_e32 v144, 0x2100, v179
	ds_read2_b64 v[170:173], v144 offset1:1
	s_waitcnt lgkmcnt(3)
	v_mfma_f32_32x32x16_bf16 v[2:17], v[192:195], v[134:137], v[2:17]
	v_add_u32_e32 v144, 0x2120, v179
	ds_read2_b64 v[192:195], v144 offset1:1
	s_waitcnt lgkmcnt(3)
	v_mfma_f32_32x32x16_bf16 v[2:17], v[196:199], v[138:141], v[2:17]
	v_add_u32_e32 v144, 0x2140, v179
	ds_read2_b64 v[196:199], v144 offset1:1
	s_waitcnt lgkmcnt(3)
	v_mfma_f32_32x32x16_bf16 v[2:17], v[218:221], v[166:169], v[2:17]
	v_add_u32_e32 v144, 0x2160, v179
	ds_read2_b64 v[218:221], v144 offset1:1
	s_waitcnt lgkmcnt(3)
	v_mfma_f32_32x32x16_bf16 v[18:33], v[170:173], v[130:133], v[18:33]
	v_add_u32_e32 v144, 0x4200, v179
	ds_read2_b64 v[170:173], v144 offset1:1
	s_waitcnt lgkmcnt(3)
	v_mfma_f32_32x32x16_bf16 v[18:33], v[192:195], v[134:137], v[18:33]
	v_add_u32_e32 v144, 0x4220, v179
	ds_read2_b64 v[192:195], v144 offset1:1
	s_waitcnt lgkmcnt(3)
	v_mfma_f32_32x32x16_bf16 v[18:33], v[196:199], v[138:141], v[18:33]
	v_add_u32_e32 v144, 0x4240, v179
	ds_read2_b64 v[196:199], v144 offset1:1
	s_waitcnt lgkmcnt(3)
	v_mfma_f32_32x32x16_bf16 v[18:33], v[218:221], v[166:169], v[18:33]
	v_add_u32_e32 v144, 0x4260, v179
	ds_read2_b64 v[218:221], v144 offset1:1
	s_waitcnt lgkmcnt(3)
	v_mfma_f32_32x32x16_bf16 v[34:49], v[170:173], v[130:133], v[34:49]
	v_add_u32_e32 v144, 0x6300, v179
	ds_read2_b64 v[170:173], v144 offset1:1
	s_waitcnt lgkmcnt(3)
	v_mfma_f32_32x32x16_bf16 v[34:49], v[192:195], v[134:137], v[34:49]
	v_add_u32_e32 v144, 0x6320, v179
	ds_read2_b64 v[192:195], v144 offset1:1
	s_waitcnt lgkmcnt(3)
	v_mfma_f32_32x32x16_bf16 v[34:49], v[196:199], v[138:141], v[34:49]
	v_add_u32_e32 v144, 0x6340, v179
	ds_read2_b64 v[196:199], v144 offset1:1
	s_waitcnt lgkmcnt(3)
	v_mfma_f32_32x32x16_bf16 v[34:49], v[218:221], v[166:169], v[34:49]
	v_add_u32_e32 v144, 0x6360, v179
	ds_read2_b64 v[218:221], v144 offset1:1
	s_waitcnt lgkmcnt(3)
	v_mfma_f32_32x32x16_bf16 v[50:65], v[170:173], v[130:133], v[50:65]
	v_add_u32_e32 v144, 0x8400, v179
	ds_read2_b64 v[170:173], v144 offset1:1
	s_waitcnt lgkmcnt(3)
	v_mfma_f32_32x32x16_bf16 v[50:65], v[192:195], v[134:137], v[50:65]
	v_add_u32_e32 v144, 0x8420, v179
	ds_read2_b64 v[192:195], v144 offset1:1
	s_waitcnt lgkmcnt(3)
	v_mfma_f32_32x32x16_bf16 v[50:65], v[196:199], v[138:141], v[50:65]
	v_add_u32_e32 v144, 0x8440, v179
	ds_read2_b64 v[196:199], v144 offset1:1
	s_waitcnt lgkmcnt(3)
	v_mfma_f32_32x32x16_bf16 v[50:65], v[218:221], v[166:169], v[50:65]
	v_add_u32_e32 v144, 0x8460, v179
	ds_read2_b64 v[218:221], v144 offset1:1
	s_waitcnt lgkmcnt(3)
	v_mfma_f32_32x32x16_bf16 v[66:81], v[170:173], v[130:133], v[66:81]
	v_add_u32_e32 v144, 0xa500, v179
	ds_read2_b64 v[170:173], v144 offset1:1
	s_waitcnt lgkmcnt(3)
	v_mfma_f32_32x32x16_bf16 v[66:81], v[192:195], v[134:137], v[66:81]
	v_add_u32_e32 v144, 0xa520, v179
	ds_read2_b64 v[192:195], v144 offset1:1
	s_waitcnt lgkmcnt(3)
	v_mfma_f32_32x32x16_bf16 v[66:81], v[196:199], v[138:141], v[66:81]
	v_add_u32_e32 v144, 0xa540, v179
	ds_read2_b64 v[196:199], v144 offset1:1
	s_waitcnt lgkmcnt(3)
	v_mfma_f32_32x32x16_bf16 v[66:81], v[218:221], v[166:169], v[66:81]
	v_add_u32_e32 v144, 0xa560, v179
	ds_read2_b64 v[218:221], v144 offset1:1
	s_waitcnt lgkmcnt(3)
	v_mfma_f32_32x32x16_bf16 v[82:97], v[170:173], v[130:133], v[82:97]
	v_add_u32_e32 v144, 0xc600, v179
	ds_read2_b64 v[170:173], v144 offset1:1
	s_waitcnt lgkmcnt(3)
	v_mfma_f32_32x32x16_bf16 v[82:97], v[192:195], v[134:137], v[82:97]
	v_add_u32_e32 v144, 0xc620, v179
	ds_read2_b64 v[192:195], v144 offset1:1
	s_waitcnt lgkmcnt(3)
	v_mfma_f32_32x32x16_bf16 v[82:97], v[196:199], v[138:141], v[82:97]
	v_add_u32_e32 v144, 0xc640, v179
	ds_read2_b64 v[196:199], v144 offset1:1
	s_waitcnt lgkmcnt(3)
	v_mfma_f32_32x32x16_bf16 v[82:97], v[218:221], v[166:169], v[82:97]
	v_add_u32_e32 v144, 0xc660, v179
	ds_read2_b64 v[218:221], v144 offset1:1
	s_waitcnt lgkmcnt(3)
	v_mfma_f32_32x32x16_bf16 v[98:113], v[170:173], v[130:133], v[98:113]
	v_add_u32_e32 v144, 0xe700, v179
	ds_read2_b64 v[170:173], v144 offset1:1
	s_waitcnt lgkmcnt(3)
	v_mfma_f32_32x32x16_bf16 v[98:113], v[192:195], v[134:137], v[98:113]
	v_add_u32_e32 v144, 0xe720, v179
	ds_read2_b64 v[192:195], v144 offset1:1
	s_waitcnt lgkmcnt(3)
	v_mfma_f32_32x32x16_bf16 v[98:113], v[196:199], v[138:141], v[98:113]
	v_add_u32_e32 v144, 0xe740, v179
	ds_read2_b64 v[196:199], v144 offset1:1
	s_waitcnt lgkmcnt(3)
	v_mfma_f32_32x32x16_bf16 v[98:113], v[218:221], v[166:169], v[98:113]
	v_add_u32_e32 v144, 0xe760, v179
	ds_read2_b64 v[218:221], v144 offset1:1
	s_waitcnt lgkmcnt(3)
	v_mfma_f32_32x32x16_bf16 v[114:129], v[170:173], v[130:133], v[114:129]
	s_waitcnt lgkmcnt(2)
	v_mfma_f32_32x32x16_bf16 v[114:129], v[192:195], v[134:137], v[114:129]
	s_waitcnt lgkmcnt(1)
	v_mfma_f32_32x32x16_bf16 v[114:129], v[196:199], v[138:141], v[114:129]
	s_waitcnt lgkmcnt(0)
	v_mfma_f32_32x32x16_bf16 v[114:129], v[218:221], v[166:169], v[114:129]
	v_fmamk_f32 v134, v191, 0x42800000, v190
	v_fmamk_f32 v135, v191, 0x42820000, v190
	v_exp_f32_e32 v134, v134
	v_exp_f32_e32 v135, v135
	v_fmamk_f32 v138, v191, 0x42a00000, v190
	v_fmamk_f32 v139, v191, 0x42a20000, v190
	v_exp_f32_e32 v138, v138
	v_exp_f32_e32 v139, v139
	v_fmamk_f32 v144, v191, 0x42c00000, v190
	v_fmamk_f32 v145, v191, 0x42c20000, v190
	v_exp_f32_e32 v144, v144
	v_exp_f32_e32 v145, v145
	v_fmamk_f32 v153, v191, 0x42e00000, v190
	s_waitcnt vmcnt(0)
	v_mov_b32_e32 v130, v234
	v_mov_b32_e32 v131, v235
	v_mov_b32_e32 v132, v236
	v_mov_b32_e32 v133, v237
	v_lshlrev_b32_e32 v136, 16, v130
	v_and_b32_e32 v137, 0xffff0000, v130
	v_pk_mul_f32 v[134:135], v[134:135], v[136:137]
	v_lshlrev_b32_e32 v136, 16, v131
	v_cvt_pk_bf16_f32 v130, v134, v135
	v_fmamk_f32 v134, v191, 0x42840000, v190
	v_fmamk_f32 v135, v191, 0x42860000, v190
	v_exp_f32_e32 v134, v134
	v_exp_f32_e32 v135, v135
	v_and_b32_e32 v137, 0xffff0000, v131
	v_pk_mul_f32 v[134:135], v[134:135], v[136:137]
	s_nop 0
	v_cvt_pk_bf16_f32 v131, v134, v135
	v_fmamk_f32 v134, v191, 0x42880000, v190
	v_fmamk_f32 v135, v191, 0x428a0000, v190
	v_exp_f32_e32 v134, v134
	v_exp_f32_e32 v135, v135
	v_lshlrev_b32_e32 v136, 16, v132
	v_and_b32_e32 v137, 0xffff0000, v132
	v_pk_mul_f32 v[134:135], v[134:135], v[136:137]
	s_nop 0
	v_cvt_pk_bf16_f32 v132, v134, v135
	v_fmamk_f32 v134, v191, 0x428c0000, v190
	v_fmamk_f32 v135, v191, 0x428e0000, v190
	v_exp_f32_e32 v134, v134
	v_exp_f32_e32 v135, v135
	v_lshlrev_b32_e32 v136, 16, v133
	v_and_b32_e32 v137, 0xffff0000, v133
	v_pk_mul_f32 v[134:135], v[134:135], v[136:137]
	s_nop 0
	v_cvt_pk_bf16_f32 v133, v134, v135
	s_waitcnt vmcnt(0)
	v_mov_b32_e32 v134, v238
	v_mov_b32_e32 v135, v239
	v_mov_b32_e32 v136, v240
	v_mov_b32_e32 v137, v241
	v_lshlrev_b32_e32 v140, 16, v134
	v_and_b32_e32 v141, 0xffff0000, v134
	v_pk_mul_f32 v[138:139], v[138:139], v[140:141]
	v_lshlrev_b32_e32 v140, 16, v135
	v_cvt_pk_bf16_f32 v134, v138, v139
	v_fmamk_f32 v138, v191, 0x42a40000, v190
	v_fmamk_f32 v139, v191, 0x42a60000, v190
	v_exp_f32_e32 v138, v138
	v_exp_f32_e32 v139, v139
	v_and_b32_e32 v141, 0xffff0000, v135
	v_pk_mul_f32 v[138:139], v[138:139], v[140:141]
	s_nop 0
	v_cvt_pk_bf16_f32 v135, v138, v139
	v_fmamk_f32 v138, v191, 0x42a80000, v190
	v_fmamk_f32 v139, v191, 0x42aa0000, v190
	v_exp_f32_e32 v138, v138
	v_exp_f32_e32 v139, v139
	v_lshlrev_b32_e32 v140, 16, v136
	v_and_b32_e32 v141, 0xffff0000, v136
	v_pk_mul_f32 v[138:139], v[138:139], v[140:141]
	s_nop 0
	v_cvt_pk_bf16_f32 v136, v138, v139
	v_fmamk_f32 v138, v191, 0x42ac0000, v190
	v_fmamk_f32 v139, v191, 0x42ae0000, v190
	v_exp_f32_e32 v138, v138
	v_exp_f32_e32 v139, v139
	v_lshlrev_b32_e32 v140, 16, v137
	v_and_b32_e32 v141, 0xffff0000, v137
	v_pk_mul_f32 v[138:139], v[138:139], v[140:141]
	s_nop 0
	v_cvt_pk_bf16_f32 v137, v138, v139
	s_waitcnt vmcnt(0)
	v_mov_b32_e32 v138, v242
	v_mov_b32_e32 v139, v243
	v_mov_b32_e32 v140, v244
	v_mov_b32_e32 v141, v245
	v_lshlrev_b32_e32 v166, 16, v138
	v_and_b32_e32 v167, 0xffff0000, v138
	v_pk_mul_f32 v[144:145], v[144:145], v[166:167]
	v_lshlrev_b32_e32 v166, 16, v139
	v_cvt_pk_bf16_f32 v138, v144, v145
	v_fmamk_f32 v144, v191, 0x42c40000, v190
	v_fmamk_f32 v145, v191, 0x42c60000, v190
	v_exp_f32_e32 v144, v144
	v_exp_f32_e32 v145, v145
	v_and_b32_e32 v167, 0xffff0000, v139
	v_pk_mul_f32 v[144:145], v[144:145], v[166:167]
	s_nop 0
	v_cvt_pk_bf16_f32 v139, v144, v145
	v_fmamk_f32 v144, v191, 0x42c80000, v190
	v_fmamk_f32 v145, v191, 0x42ca0000, v190
	v_exp_f32_e32 v144, v144
	v_exp_f32_e32 v145, v145
	v_lshlrev_b32_e32 v166, 16, v140
	v_and_b32_e32 v167, 0xffff0000, v140
	v_pk_mul_f32 v[144:145], v[144:145], v[166:167]
	s_nop 0
	v_cvt_pk_bf16_f32 v140, v144, v145
	v_fmamk_f32 v144, v191, 0x42cc0000, v190
	v_fmamk_f32 v145, v191, 0x42ce0000, v190
	v_exp_f32_e32 v144, v144
	v_exp_f32_e32 v145, v145
	v_lshlrev_b32_e32 v166, 16, v141
	v_and_b32_e32 v167, 0xffff0000, v141
	v_pk_mul_f32 v[144:145], v[144:145], v[166:167]
	s_nop 0
	v_cvt_pk_bf16_f32 v141, v144, v145
	v_exp_f32_e32 v166, v153
	v_fmamk_f32 v153, v191, 0x42e20000, v190
	v_exp_f32_e32 v167, v153
	v_fmamk_f32 v153, v191, 0x42e40000, v190
	s_waitcnt vmcnt(0)
	v_mov_b32_e32 v142, v246
	v_mov_b32_e32 v143, v247
	v_mov_b32_e32 v144, v248
	v_mov_b32_e32 v145, v249
	v_lshlrev_b32_e32 v168, 16, v142
	v_and_b32_e32 v169, 0xffff0000, v142
	v_pk_mul_f32 v[166:167], v[166:167], v[168:169]
	v_lshlrev_b32_e32 v168, 16, v143
	v_cvt_pk_bf16_f32 v142, v166, v167
	v_exp_f32_e32 v166, v153
	v_fmamk_f32 v153, v191, 0x42e60000, v190
	v_exp_f32_e32 v167, v153
	v_and_b32_e32 v169, 0xffff0000, v143
	v_fmamk_f32 v153, v191, 0x42e80000, v190
	v_pk_mul_f32 v[166:167], v[166:167], v[168:169]
	s_nop 0
	v_cvt_pk_bf16_f32 v143, v166, v167
	v_exp_f32_e32 v166, v153
	v_fmamk_f32 v153, v191, 0x42ea0000, v190
	v_exp_f32_e32 v167, v153
	v_lshlrev_b32_e32 v168, 16, v144
	v_and_b32_e32 v169, 0xffff0000, v144
	v_fmamk_f32 v153, v191, 0x42ec0000, v190
	v_pk_mul_f32 v[166:167], v[166:167], v[168:169]
	v_fmac_f32_e32 v190, 0x42ee0000, v191
	v_cvt_pk_bf16_f32 v144, v166, v167
	v_exp_f32_e32 v166, v153
	v_exp_f32_e32 v167, v190
	v_lshlrev_b32_e32 v168, 16, v145
	v_and_b32_e32 v169, 0xffff0000, v145
	v_pk_mul_f32 v[166:167], v[166:167], v[168:169]
	s_nop 0
	v_cvt_pk_bf16_f32 v145, v166, v167
	ds_read2_b64 v[166:169], v179 offset0:16 offset1:17
	ds_read2_b64 v[170:173], v179 offset0:20 offset1:21
	ds_read2_b64 v[190:193], v179 offset0:24 offset1:25
	ds_read2_b64 v[194:197], v179 offset0:28 offset1:29
	s_waitcnt lgkmcnt(3)
	v_mfma_f32_32x32x16_bf16 v[2:17], v[166:169], v[130:133], v[2:17]
	v_add_u32_e32 v153, 0x2180, v179
	ds_read2_b64 v[166:169], v153 offset1:1
	s_waitcnt lgkmcnt(3)
	v_mfma_f32_32x32x16_bf16 v[2:17], v[170:173], v[134:137], v[2:17]
	v_add_u32_e32 v153, 0x21a0, v179
	ds_read2_b64 v[170:173], v153 offset1:1
	s_waitcnt lgkmcnt(3)
	v_mfma_f32_32x32x16_bf16 v[2:17], v[190:193], v[138:141], v[2:17]
	v_add_u32_e32 v153, 0x21c0, v179
	ds_read2_b64 v[190:193], v153 offset1:1
	s_waitcnt lgkmcnt(3)
	v_mfma_f32_32x32x16_bf16 v[2:17], v[194:197], v[142:145], v[2:17]
	v_add_u32_e32 v153, 0x21e0, v179
	ds_read2_b64 v[194:197], v153 offset1:1
	s_waitcnt lgkmcnt(3)
	v_mfma_f32_32x32x16_bf16 v[18:33], v[166:169], v[130:133], v[18:33]
	v_add_u32_e32 v153, 0x4280, v179
	ds_read2_b64 v[166:169], v153 offset1:1
	s_waitcnt lgkmcnt(3)
	v_mfma_f32_32x32x16_bf16 v[18:33], v[170:173], v[134:137], v[18:33]
	v_add_u32_e32 v153, 0x42a0, v179
	ds_read2_b64 v[170:173], v153 offset1:1
	s_waitcnt lgkmcnt(3)
	v_mfma_f32_32x32x16_bf16 v[18:33], v[190:193], v[138:141], v[18:33]
	v_add_u32_e32 v153, 0x42c0, v179
	ds_read2_b64 v[190:193], v153 offset1:1
	s_waitcnt lgkmcnt(3)
	v_mfma_f32_32x32x16_bf16 v[18:33], v[194:197], v[142:145], v[18:33]
	v_add_u32_e32 v153, 0x42e0, v179
	ds_read2_b64 v[194:197], v153 offset1:1
	s_waitcnt lgkmcnt(3)
	v_mfma_f32_32x32x16_bf16 v[34:49], v[166:169], v[130:133], v[34:49]
	v_add_u32_e32 v153, 0x6380, v179
	ds_read2_b64 v[166:169], v153 offset1:1
	s_waitcnt lgkmcnt(3)
	v_mfma_f32_32x32x16_bf16 v[34:49], v[170:173], v[134:137], v[34:49]
	v_add_u32_e32 v153, 0x63a0, v179
	ds_read2_b64 v[170:173], v153 offset1:1
	s_waitcnt lgkmcnt(3)
	v_mfma_f32_32x32x16_bf16 v[34:49], v[190:193], v[138:141], v[34:49]
	v_add_u32_e32 v153, 0x63c0, v179
	ds_read2_b64 v[190:193], v153 offset1:1
	s_waitcnt lgkmcnt(3)
	v_mfma_f32_32x32x16_bf16 v[34:49], v[194:197], v[142:145], v[34:49]
	v_add_u32_e32 v153, 0x63e0, v179
	ds_read2_b64 v[194:197], v153 offset1:1
	s_waitcnt lgkmcnt(3)
	v_mfma_f32_32x32x16_bf16 v[50:65], v[166:169], v[130:133], v[50:65]
	v_add_u32_e32 v153, 0x8480, v179
	ds_read2_b64 v[166:169], v153 offset1:1
	s_waitcnt lgkmcnt(3)
	v_mfma_f32_32x32x16_bf16 v[50:65], v[170:173], v[134:137], v[50:65]
	v_add_u32_e32 v153, 0x84a0, v179
	ds_read2_b64 v[170:173], v153 offset1:1
	s_waitcnt lgkmcnt(3)
	v_mfma_f32_32x32x16_bf16 v[50:65], v[190:193], v[138:141], v[50:65]
	v_add_u32_e32 v153, 0x84c0, v179
	ds_read2_b64 v[190:193], v153 offset1:1
	s_waitcnt lgkmcnt(3)
	v_mfma_f32_32x32x16_bf16 v[50:65], v[194:197], v[142:145], v[50:65]
	v_add_u32_e32 v153, 0x84e0, v179
	ds_read2_b64 v[194:197], v153 offset1:1
	s_waitcnt lgkmcnt(3)
	v_mfma_f32_32x32x16_bf16 v[66:81], v[166:169], v[130:133], v[66:81]
	v_add_u32_e32 v153, 0xa580, v179
	ds_read2_b64 v[166:169], v153 offset1:1
	s_waitcnt lgkmcnt(3)
	v_mfma_f32_32x32x16_bf16 v[66:81], v[170:173], v[134:137], v[66:81]
	v_add_u32_e32 v153, 0xa5a0, v179
	ds_read2_b64 v[170:173], v153 offset1:1
	s_waitcnt lgkmcnt(3)
	v_mfma_f32_32x32x16_bf16 v[66:81], v[190:193], v[138:141], v[66:81]
	v_add_u32_e32 v153, 0xa5c0, v179
	ds_read2_b64 v[190:193], v153 offset1:1
	s_waitcnt lgkmcnt(3)
	v_mfma_f32_32x32x16_bf16 v[66:81], v[194:197], v[142:145], v[66:81]
	v_add_u32_e32 v153, 0xa5e0, v179
	ds_read2_b64 v[194:197], v153 offset1:1
	s_waitcnt lgkmcnt(3)
	v_mfma_f32_32x32x16_bf16 v[82:97], v[166:169], v[130:133], v[82:97]
	v_add_u32_e32 v153, 0xc680, v179
	ds_read2_b64 v[166:169], v153 offset1:1
	s_waitcnt lgkmcnt(3)
	v_mfma_f32_32x32x16_bf16 v[82:97], v[170:173], v[134:137], v[82:97]
	v_add_u32_e32 v153, 0xc6a0, v179
	ds_read2_b64 v[170:173], v153 offset1:1
	s_waitcnt lgkmcnt(3)
	v_mfma_f32_32x32x16_bf16 v[82:97], v[190:193], v[138:141], v[82:97]
	v_add_u32_e32 v153, 0xc6c0, v179
	ds_read2_b64 v[190:193], v153 offset1:1
	s_waitcnt lgkmcnt(3)
	v_mfma_f32_32x32x16_bf16 v[82:97], v[194:197], v[142:145], v[82:97]
	v_add_u32_e32 v153, 0xc6e0, v179
	ds_read2_b64 v[194:197], v153 offset1:1
	s_waitcnt lgkmcnt(3)
	v_mfma_f32_32x32x16_bf16 v[98:113], v[166:169], v[130:133], v[98:113]
	v_add_u32_e32 v153, 0xe780, v179
	ds_read2_b64 v[166:169], v153 offset1:1
	s_waitcnt lgkmcnt(3)
	v_mfma_f32_32x32x16_bf16 v[98:113], v[170:173], v[134:137], v[98:113]
	v_add_u32_e32 v153, 0xe7a0, v179
	ds_read2_b64 v[170:173], v153 offset1:1
	s_waitcnt lgkmcnt(3)
	v_mfma_f32_32x32x16_bf16 v[98:113], v[190:193], v[138:141], v[98:113]
	v_add_u32_e32 v153, 0xe7c0, v179
	ds_read2_b64 v[190:193], v153 offset1:1
	s_waitcnt lgkmcnt(3)
	v_mfma_f32_32x32x16_bf16 v[98:113], v[194:197], v[142:145], v[98:113]
	v_add_u32_e32 v153, 0xe7e0, v179
	ds_read2_b64 v[194:197], v153 offset1:1
	s_waitcnt lgkmcnt(3)
	v_mfma_f32_32x32x16_bf16 v[114:129], v[166:169], v[130:133], v[114:129]
	s_waitcnt lgkmcnt(2)
	v_mfma_f32_32x32x16_bf16 v[114:129], v[170:173], v[134:137], v[114:129]
	s_waitcnt lgkmcnt(1)
	v_mfma_f32_32x32x16_bf16 v[114:129], v[190:193], v[138:141], v[114:129]
	s_waitcnt lgkmcnt(0)
	v_mfma_f32_32x32x16_bf16 v[114:129], v[194:197], v[142:145], v[114:129]
	s_add_i32 s66, s66, 1
	s_add_i32 s67, s67, -1
	s_cmp_eq_u32 s67, -1
	s_cbranch_scc0 .LBB0_327
	s_and_b64 vcc, exec, s[4:5]
	s_mov_b64 s[4:5], -1
	s_cbranch_vccnz .LBB0_330
	s_mov_b64 s[4:5], 0
